# P17 FFN-down epilogue fused with final LayerNorm: U kept in registers, per-row (mean,M2) partials exchanged among the 4 column-tile workgroups via write-through stores + arrival counter, final LN appl
# speedup vs baseline: 1.0794x; 1.0116x over previous
.LBB0_1984:
	v_lshlrev_b32_e32 v130, 3, v153
	v_and_b32_e32 v190, 0x78, v130
	v_ashrrev_i32_e32 v152, 4, v153
	v_lshrrev_b32_e32 v130, 1, v153
	v_and_b32_e32 v191, 0x60, v130
	v_or_b32_e32 v130, 4, v190
	v_lshlrev_b32_e32 v132, 2, v152
	v_bitop3_b32 v133, v132, v190, 48 bitop3:0x6c
	v_bitop3_b32 v132, v132, v130, 48 bitop3:0x6c
	v_lshlrev_b32_e32 v134, 9, v152
	v_lshlrev_b32_e32 v132, 2, v132
	v_add_u32_e32 v151, 32, v152
	v_lshlrev_b32_e32 v133, 2, v133
	v_add3_u32 v148, s44, v132, v134
	v_lshlrev_b32_e32 v132, 2, v151
	v_add3_u32 v147, s44, v133, v134
	v_bitop3_b32 v133, v132, v190, 48 bitop3:0x6c
	v_bitop3_b32 v132, v132, v130, 48 bitop3:0x6c
	v_lshlrev_b32_e32 v134, 9, v151
	v_lshlrev_b32_e32 v132, 2, v132
	v_add_u32_e32 v150, 64, v152
	v_lshlrev_b32_e32 v133, 2, v133
	v_add3_u32 v145, s44, v132, v134
	v_lshlrev_b32_e32 v132, 2, v150
	v_add3_u32 v146, s44, v133, v134
	v_bitop3_b32 v133, v132, v190, 48 bitop3:0x6c
	v_bitop3_b32 v132, v132, v130, 48 bitop3:0x6c
	v_lshlrev_b32_e32 v134, 9, v150
	v_lshlrev_b32_e32 v132, 2, v132
	v_add_u32_e32 v149, 0x60, v152
	v_lshlrev_b32_e32 v133, 2, v133
	v_add3_u32 v143, s44, v132, v134
	v_lshlrev_b32_e32 v132, 2, v149
	v_add3_u32 v144, s44, v133, v134
	v_bitop3_b32 v133, v132, v190, 48 bitop3:0x6c
	v_bitop3_b32 v130, v132, v130, 48 bitop3:0x6c
	v_lshlrev_b32_e32 v133, 2, v133
	v_lshlrev_b32_e32 v134, 9, v149
	v_lshlrev_b32_e32 v130, 2, v130
	s_lshl_b64 s[38:39], s[36:37], 2
	v_add3_u32 v141, s44, v133, v134
	v_add3_u32 v140, s44, v130, v134
	v_bfe_u32 v189, v153, 4, 2
	v_and_b32_e32 v188, 15, v153
	v_lshlrev_b32_e32 v193, 4, v189
	v_lshlrev_b32_e32 v153, 7, v153
	v_or_b32_e32 v192, v191, v188
	v_bitop3_b32 v188, v191, v193, v188 bitop3:0x36
	v_and_b32_e32 v153, 0xffff8000, v153
	v_lshlrev_b32_e32 v188, 2, v188
	v_lshl_or_b32 v189, v189, 11, v153
	v_add3_u32 v153, s44, v188, v189
	v_bitop3_b32 v252, v192, v193, 16 bitop3:0x36
	v_lshlrev_b32_e32 v252, 2, v252
	v_add3_u32 v252, s44, v252, v189
	v_lshrrev_b32_e32 v220, 4, v0
	v_add_u32_e32 v220, s49, v220
	v_and_b32_e32 v222, 15, v0
	v_lshlrev_b32_e32 v222, 5, v222
	s_lshl_b32 s2, s36, 2
	v_add_u32_e32 v222, s2, v222
	v_mov_b32_e32 v223, 0
	v_mov_b32_e32 v221, 0
	v_lshlrev_b64 v[224:225], 12, v[220:221]
	v_lshl_add_u64 v[224:225], v[224:225], 0, v[222:223]
	v_lshl_add_u64 v[226:227], s[66:67], 0, v[224:225]
	v_lshlrev_b32_e32 v228, 3, v220
	v_mov_b32_e32 v229, 0
	s_add_u32 s2, s62, 0xf000000
	s_addc_u32 s3, s63, 0
	v_lshl_add_u64 v[228:229], s[2:3], 0, v[228:229]
	v_readlane_b32 s2, v253, 46
	v_readlane_b32 s3, v253, 47
	s_nop 1
	v_lshl_add_u64 v[230:231], s[2:3], 0, v[222:223]
	v_readlane_b32 s2, v255, 40
	v_readlane_b32 s3, v255, 41
	s_nop 1
	v_lshl_add_u64 v[232:233], s[2:3], 0, v[222:223]
	s_mov_b32 s4, 0x20000
	s_mov_b32 s5, 0
	s_mov_b32 s6, 0x40000
	s_mov_b32 s7, 0
	s_mov_b32 s8, 0x60000
	s_mov_b32 s9, 0
	s_mov_b32 s11, 0
	s_mov_b32 s10, 0x0
	v_lshl_add_u64 v[150:151], v[226:227], 0, s[10:11]
	global_load_dwordx2 v[138:139], v[228:229], off offset:0
	global_load_dwordx2 v[246:247], v[228:229], off offset:256
	global_load_dwordx2 v[248:249], v[228:229], off offset:512
	global_load_dwordx2 v[250:251], v[228:229], off offset:768
	global_load_dwordx4 v[130:133], v[230:231], off offset:0
	global_load_dwordx4 v[134:137], v[230:231], off offset:16
	global_load_dwordx4 v[238:241], v[232:233], off offset:0
	global_load_dwordx4 v[242:245], v[232:233], off offset:16
	global_load_dwordx4 v[186:189], v[150:151], off
	global_load_dwordx4 v[190:193], v[150:151], off offset:16
	v_lshl_add_u64 v[218:219], v[150:151], 0, s[4:5]
	global_load_dwordx4 v[194:197], v[218:219], off
	global_load_dwordx4 v[198:201], v[218:219], off offset:16
	v_lshl_add_u64 v[218:219], v[150:151], 0, s[6:7]
	global_load_dwordx4 v[202:205], v[218:219], off
	global_load_dwordx4 v[206:209], v[218:219], off offset:16
	v_lshl_add_u64 v[218:219], v[150:151], 0, s[8:9]
	global_load_dwordx4 v[210:213], v[218:219], off
	global_load_dwordx4 v[214:217], v[218:219], off offset:16
	ds_write2st64_b32 v153, v126, v127 offset1:2
	ds_write2st64_b32 v153, v128, v129 offset0:4 offset1:6
	ds_write2st64_b32 v252, v98, v99 offset1:2
	ds_write2st64_b32 v252, v100, v101 offset0:4 offset1:6
	ds_write2st64_b32 v153, v102, v103 offset0:32 offset1:34
	ds_write2st64_b32 v153, v104, v105 offset0:36 offset1:38
	ds_write2st64_b32 v252, v106, v107 offset0:32 offset1:34
	ds_write2st64_b32 v252, v108, v109 offset0:36 offset1:38
	ds_write2st64_b32 v153, v110, v111 offset0:64 offset1:66
	ds_write2st64_b32 v153, v112, v113 offset0:68 offset1:70
	ds_write2st64_b32 v252, v114, v115 offset0:64 offset1:66
	ds_write2st64_b32 v252, v116, v117 offset0:68 offset1:70
	ds_write2st64_b32 v153, v118, v119 offset0:96 offset1:98
	ds_write2st64_b32 v153, v120, v121 offset0:100 offset1:102
	ds_write2st64_b32 v252, v122, v123 offset0:96 offset1:98
	ds_write2st64_b32 v252, v124, v125 offset0:100 offset1:102
	s_waitcnt lgkmcnt(0)
	s_barrier
	ds_read_b128 v[154:157], v147
	ds_read_b128 v[158:161], v148
	ds_read_b128 v[162:165], v146
	ds_read_b128 v[166:169], v145
	ds_read_b128 v[170:173], v144
	ds_read_b128 v[174:177], v143
	ds_read_b128 v[178:181], v141
	ds_read_b128 v[182:185], v140
	s_waitcnt vmcnt(0) lgkmcnt(0)
	s_barrier
	v_pk_add_f32 v[186:187], v[186:187], v[138:139] op_sel_hi:[1,0] neg_lo:[0,1] neg_hi:[0,1]
	v_pk_mul_f32 v[186:187], v[186:187], v[138:139] op_sel:[0,1]
	v_pk_fma_f32 v[186:187], v[130:131], v[186:187], v[238:239]
	v_pk_fma_f32 v[98:99], v[186:187], s[30:31], v[154:155] op_sel_hi:[1,0,1]
	v_pk_add_f32 v[188:189], v[188:189], v[138:139] op_sel_hi:[1,0] neg_lo:[0,1] neg_hi:[0,1]
	v_pk_mul_f32 v[188:189], v[188:189], v[138:139] op_sel:[0,1]
	v_pk_fma_f32 v[188:189], v[132:133], v[188:189], v[240:241]
	v_pk_fma_f32 v[100:101], v[188:189], s[30:31], v[156:157] op_sel_hi:[1,0,1]
	v_pk_add_f32 v[190:191], v[190:191], v[138:139] op_sel_hi:[1,0] neg_lo:[0,1] neg_hi:[0,1]
	v_pk_mul_f32 v[190:191], v[190:191], v[138:139] op_sel:[0,1]
	v_pk_fma_f32 v[190:191], v[134:135], v[190:191], v[242:243]
	v_pk_fma_f32 v[102:103], v[190:191], s[30:31], v[158:159] op_sel_hi:[1,0,1]
	v_pk_add_f32 v[192:193], v[192:193], v[138:139] op_sel_hi:[1,0] neg_lo:[0,1] neg_hi:[0,1]
	v_pk_mul_f32 v[192:193], v[192:193], v[138:139] op_sel:[0,1]
	v_pk_fma_f32 v[192:193], v[136:137], v[192:193], v[244:245]
	v_pk_fma_f32 v[104:105], v[192:193], s[30:31], v[160:161] op_sel_hi:[1,0,1]
	v_pk_add_f32 v[194:195], v[194:195], v[246:247] op_sel_hi:[1,0] neg_lo:[0,1] neg_hi:[0,1]
	v_pk_mul_f32 v[194:195], v[194:195], v[246:247] op_sel:[0,1]
	v_pk_fma_f32 v[194:195], v[130:131], v[194:195], v[238:239]
	v_pk_fma_f32 v[106:107], v[194:195], s[30:31], v[162:163] op_sel_hi:[1,0,1]
	v_pk_add_f32 v[196:197], v[196:197], v[246:247] op_sel_hi:[1,0] neg_lo:[0,1] neg_hi:[0,1]
	v_pk_mul_f32 v[196:197], v[196:197], v[246:247] op_sel:[0,1]
	v_pk_fma_f32 v[196:197], v[132:133], v[196:197], v[240:241]
	v_pk_fma_f32 v[108:109], v[196:197], s[30:31], v[164:165] op_sel_hi:[1,0,1]
	v_pk_add_f32 v[198:199], v[198:199], v[246:247] op_sel_hi:[1,0] neg_lo:[0,1] neg_hi:[0,1]
	v_pk_mul_f32 v[198:199], v[198:199], v[246:247] op_sel:[0,1]
	v_pk_fma_f32 v[198:199], v[134:135], v[198:199], v[242:243]
	v_pk_fma_f32 v[110:111], v[198:199], s[30:31], v[166:167] op_sel_hi:[1,0,1]
	v_pk_add_f32 v[200:201], v[200:201], v[246:247] op_sel_hi:[1,0] neg_lo:[0,1] neg_hi:[0,1]
	v_pk_mul_f32 v[200:201], v[200:201], v[246:247] op_sel:[0,1]
	v_pk_fma_f32 v[200:201], v[136:137], v[200:201], v[244:245]
	v_pk_fma_f32 v[112:113], v[200:201], s[30:31], v[168:169] op_sel_hi:[1,0,1]
	v_pk_add_f32 v[202:203], v[202:203], v[248:249] op_sel_hi:[1,0] neg_lo:[0,1] neg_hi:[0,1]
	v_pk_mul_f32 v[202:203], v[202:203], v[248:249] op_sel:[0,1]
	v_pk_fma_f32 v[202:203], v[130:131], v[202:203], v[238:239]
	v_pk_fma_f32 v[114:115], v[202:203], s[30:31], v[170:171] op_sel_hi:[1,0,1]
	v_pk_add_f32 v[204:205], v[204:205], v[248:249] op_sel_hi:[1,0] neg_lo:[0,1] neg_hi:[0,1]
	v_pk_mul_f32 v[204:205], v[204:205], v[248:249] op_sel:[0,1]
	v_pk_fma_f32 v[204:205], v[132:133], v[204:205], v[240:241]
	v_pk_fma_f32 v[116:117], v[204:205], s[30:31], v[172:173] op_sel_hi:[1,0,1]
	v_pk_add_f32 v[206:207], v[206:207], v[248:249] op_sel_hi:[1,0] neg_lo:[0,1] neg_hi:[0,1]
	v_pk_mul_f32 v[206:207], v[206:207], v[248:249] op_sel:[0,1]
	v_pk_fma_f32 v[206:207], v[134:135], v[206:207], v[242:243]
	v_pk_fma_f32 v[118:119], v[206:207], s[30:31], v[174:175] op_sel_hi:[1,0,1]
	v_pk_add_f32 v[208:209], v[208:209], v[248:249] op_sel_hi:[1,0] neg_lo:[0,1] neg_hi:[0,1]
	v_pk_mul_f32 v[208:209], v[208:209], v[248:249] op_sel:[0,1]
	v_pk_fma_f32 v[208:209], v[136:137], v[208:209], v[244:245]
	v_pk_fma_f32 v[120:121], v[208:209], s[30:31], v[176:177] op_sel_hi:[1,0,1]
	v_pk_add_f32 v[210:211], v[210:211], v[250:251] op_sel_hi:[1,0] neg_lo:[0,1] neg_hi:[0,1]
	v_pk_mul_f32 v[210:211], v[210:211], v[250:251] op_sel:[0,1]
	v_pk_fma_f32 v[210:211], v[130:131], v[210:211], v[238:239]
	v_pk_fma_f32 v[122:123], v[210:211], s[30:31], v[178:179] op_sel_hi:[1,0,1]
	v_pk_add_f32 v[212:213], v[212:213], v[250:251] op_sel_hi:[1,0] neg_lo:[0,1] neg_hi:[0,1]
	v_pk_mul_f32 v[212:213], v[212:213], v[250:251] op_sel:[0,1]
	v_pk_fma_f32 v[212:213], v[132:133], v[212:213], v[240:241]
	v_pk_fma_f32 v[124:125], v[212:213], s[30:31], v[180:181] op_sel_hi:[1,0,1]
	v_pk_add_f32 v[214:215], v[214:215], v[250:251] op_sel_hi:[1,0] neg_lo:[0,1] neg_hi:[0,1]
	v_pk_mul_f32 v[214:215], v[214:215], v[250:251] op_sel:[0,1]
	v_pk_fma_f32 v[214:215], v[134:135], v[214:215], v[242:243]
	v_pk_fma_f32 v[126:127], v[214:215], s[30:31], v[182:183] op_sel_hi:[1,0,1]
	v_pk_add_f32 v[216:217], v[216:217], v[250:251] op_sel_hi:[1,0] neg_lo:[0,1] neg_hi:[0,1]
	v_pk_mul_f32 v[216:217], v[216:217], v[250:251] op_sel:[0,1]
	v_pk_fma_f32 v[216:217], v[136:137], v[216:217], v[244:245]
	v_pk_fma_f32 v[128:129], v[216:217], s[30:31], v[184:185] op_sel_hi:[1,0,1]
	s_mov_b32 s10, 0x200
	v_lshl_add_u64 v[150:151], v[226:227], 0, s[10:11]
	global_load_dwordx2 v[138:139], v[228:229], off offset:0
	global_load_dwordx2 v[246:247], v[228:229], off offset:256
	global_load_dwordx2 v[248:249], v[228:229], off offset:512
	global_load_dwordx2 v[250:251], v[228:229], off offset:768
	global_load_dwordx4 v[130:133], v[230:231], off offset:512
	global_load_dwordx4 v[134:137], v[230:231], off offset:528
	global_load_dwordx4 v[238:241], v[232:233], off offset:512
	global_load_dwordx4 v[242:245], v[232:233], off offset:528
	global_load_dwordx4 v[186:189], v[150:151], off
	global_load_dwordx4 v[190:193], v[150:151], off offset:16
	v_lshl_add_u64 v[218:219], v[150:151], 0, s[4:5]
	global_load_dwordx4 v[194:197], v[218:219], off
	global_load_dwordx4 v[198:201], v[218:219], off offset:16
	v_lshl_add_u64 v[218:219], v[150:151], 0, s[6:7]
	global_load_dwordx4 v[202:205], v[218:219], off
	global_load_dwordx4 v[206:209], v[218:219], off offset:16
	v_lshl_add_u64 v[218:219], v[150:151], 0, s[8:9]
	global_load_dwordx4 v[210:213], v[218:219], off
	global_load_dwordx4 v[214:217], v[218:219], off offset:16
	ds_write2st64_b32 v153, v66, v67 offset1:2
	ds_write2st64_b32 v153, v68, v69 offset0:4 offset1:6
	ds_write2st64_b32 v252, v70, v71 offset1:2
	ds_write2st64_b32 v252, v72, v73 offset0:4 offset1:6
	ds_write2st64_b32 v153, v74, v75 offset0:32 offset1:34
	ds_write2st64_b32 v153, v76, v77 offset0:36 offset1:38
	ds_write2st64_b32 v252, v78, v79 offset0:32 offset1:34
	ds_write2st64_b32 v252, v80, v81 offset0:36 offset1:38
	ds_write2st64_b32 v153, v82, v83 offset0:64 offset1:66
	ds_write2st64_b32 v153, v84, v85 offset0:68 offset1:70
	ds_write2st64_b32 v252, v86, v87 offset0:64 offset1:66
	ds_write2st64_b32 v252, v88, v89 offset0:68 offset1:70
	ds_write2st64_b32 v153, v90, v91 offset0:96 offset1:98
	ds_write2st64_b32 v153, v92, v93 offset0:100 offset1:102
	ds_write2st64_b32 v252, v94, v95 offset0:96 offset1:98
	ds_write2st64_b32 v252, v96, v97 offset0:100 offset1:102
	s_waitcnt lgkmcnt(0)
	s_barrier
	ds_read_b128 v[154:157], v147
	ds_read_b128 v[158:161], v148
	ds_read_b128 v[162:165], v146
	ds_read_b128 v[166:169], v145
	ds_read_b128 v[170:173], v144
	ds_read_b128 v[174:177], v143
	ds_read_b128 v[178:181], v141
	ds_read_b128 v[182:185], v140
	s_waitcnt vmcnt(0) lgkmcnt(0)
	s_barrier
	v_pk_add_f32 v[186:187], v[186:187], v[138:139] op_sel_hi:[1,0] neg_lo:[0,1] neg_hi:[0,1]
	v_pk_mul_f32 v[186:187], v[186:187], v[138:139] op_sel:[0,1]
	v_pk_fma_f32 v[186:187], v[130:131], v[186:187], v[238:239]
	v_pk_fma_f32 v[66:67], v[186:187], s[30:31], v[154:155] op_sel_hi:[1,0,1]
	v_pk_add_f32 v[188:189], v[188:189], v[138:139] op_sel_hi:[1,0] neg_lo:[0,1] neg_hi:[0,1]
	v_pk_mul_f32 v[188:189], v[188:189], v[138:139] op_sel:[0,1]
	v_pk_fma_f32 v[188:189], v[132:133], v[188:189], v[240:241]
	v_pk_fma_f32 v[68:69], v[188:189], s[30:31], v[156:157] op_sel_hi:[1,0,1]
	v_pk_add_f32 v[190:191], v[190:191], v[138:139] op_sel_hi:[1,0] neg_lo:[0,1] neg_hi:[0,1]
	v_pk_mul_f32 v[190:191], v[190:191], v[138:139] op_sel:[0,1]
	v_pk_fma_f32 v[190:191], v[134:135], v[190:191], v[242:243]
	v_pk_fma_f32 v[70:71], v[190:191], s[30:31], v[158:159] op_sel_hi:[1,0,1]
	v_pk_add_f32 v[192:193], v[192:193], v[138:139] op_sel_hi:[1,0] neg_lo:[0,1] neg_hi:[0,1]
	v_pk_mul_f32 v[192:193], v[192:193], v[138:139] op_sel:[0,1]
	v_pk_fma_f32 v[192:193], v[136:137], v[192:193], v[244:245]
	v_pk_fma_f32 v[72:73], v[192:193], s[30:31], v[160:161] op_sel_hi:[1,0,1]
	v_pk_add_f32 v[194:195], v[194:195], v[246:247] op_sel_hi:[1,0] neg_lo:[0,1] neg_hi:[0,1]
	v_pk_mul_f32 v[194:195], v[194:195], v[246:247] op_sel:[0,1]
	v_pk_fma_f32 v[194:195], v[130:131], v[194:195], v[238:239]
	v_pk_fma_f32 v[74:75], v[194:195], s[30:31], v[162:163] op_sel_hi:[1,0,1]
	v_pk_add_f32 v[196:197], v[196:197], v[246:247] op_sel_hi:[1,0] neg_lo:[0,1] neg_hi:[0,1]
	v_pk_mul_f32 v[196:197], v[196:197], v[246:247] op_sel:[0,1]
	v_pk_fma_f32 v[196:197], v[132:133], v[196:197], v[240:241]
	v_pk_fma_f32 v[76:77], v[196:197], s[30:31], v[164:165] op_sel_hi:[1,0,1]
	v_pk_add_f32 v[198:199], v[198:199], v[246:247] op_sel_hi:[1,0] neg_lo:[0,1] neg_hi:[0,1]
	v_pk_mul_f32 v[198:199], v[198:199], v[246:247] op_sel:[0,1]
	v_pk_fma_f32 v[198:199], v[134:135], v[198:199], v[242:243]
	v_pk_fma_f32 v[78:79], v[198:199], s[30:31], v[166:167] op_sel_hi:[1,0,1]
	v_pk_add_f32 v[200:201], v[200:201], v[246:247] op_sel_hi:[1,0] neg_lo:[0,1] neg_hi:[0,1]
	v_pk_mul_f32 v[200:201], v[200:201], v[246:247] op_sel:[0,1]
	v_pk_fma_f32 v[200:201], v[136:137], v[200:201], v[244:245]
	v_pk_fma_f32 v[80:81], v[200:201], s[30:31], v[168:169] op_sel_hi:[1,0,1]
	v_pk_add_f32 v[202:203], v[202:203], v[248:249] op_sel_hi:[1,0] neg_lo:[0,1] neg_hi:[0,1]
	v_pk_mul_f32 v[202:203], v[202:203], v[248:249] op_sel:[0,1]
	v_pk_fma_f32 v[202:203], v[130:131], v[202:203], v[238:239]
	v_pk_fma_f32 v[82:83], v[202:203], s[30:31], v[170:171] op_sel_hi:[1,0,1]
	v_pk_add_f32 v[204:205], v[204:205], v[248:249] op_sel_hi:[1,0] neg_lo:[0,1] neg_hi:[0,1]
	v_pk_mul_f32 v[204:205], v[204:205], v[248:249] op_sel:[0,1]
	v_pk_fma_f32 v[204:205], v[132:133], v[204:205], v[240:241]
	v_pk_fma_f32 v[84:85], v[204:205], s[30:31], v[172:173] op_sel_hi:[1,0,1]
	v_pk_add_f32 v[206:207], v[206:207], v[248:249] op_sel_hi:[1,0] neg_lo:[0,1] neg_hi:[0,1]
	v_pk_mul_f32 v[206:207], v[206:207], v[248:249] op_sel:[0,1]
	v_pk_fma_f32 v[206:207], v[134:135], v[206:207], v[242:243]
	v_pk_fma_f32 v[86:87], v[206:207], s[30:31], v[174:175] op_sel_hi:[1,0,1]
	v_pk_add_f32 v[208:209], v[208:209], v[248:249] op_sel_hi:[1,0] neg_lo:[0,1] neg_hi:[0,1]
	v_pk_mul_f32 v[208:209], v[208:209], v[248:249] op_sel:[0,1]
	v_pk_fma_f32 v[208:209], v[136:137], v[208:209], v[244:245]
	v_pk_fma_f32 v[88:89], v[208:209], s[30:31], v[176:177] op_sel_hi:[1,0,1]
	v_pk_add_f32 v[210:211], v[210:211], v[250:251] op_sel_hi:[1,0] neg_lo:[0,1] neg_hi:[0,1]
	v_pk_mul_f32 v[210:211], v[210:211], v[250:251] op_sel:[0,1]
	v_pk_fma_f32 v[210:211], v[130:131], v[210:211], v[238:239]
	v_pk_fma_f32 v[90:91], v[210:211], s[30:31], v[178:179] op_sel_hi:[1,0,1]
	v_pk_add_f32 v[212:213], v[212:213], v[250:251] op_sel_hi:[1,0] neg_lo:[0,1] neg_hi:[0,1]
	v_pk_mul_f32 v[212:213], v[212:213], v[250:251] op_sel:[0,1]
	v_pk_fma_f32 v[212:213], v[132:133], v[212:213], v[240:241]
	v_pk_fma_f32 v[92:93], v[212:213], s[30:31], v[180:181] op_sel_hi:[1,0,1]
	v_pk_add_f32 v[214:215], v[214:215], v[250:251] op_sel_hi:[1,0] neg_lo:[0,1] neg_hi:[0,1]
	v_pk_mul_f32 v[214:215], v[214:215], v[250:251] op_sel:[0,1]
	v_pk_fma_f32 v[214:215], v[134:135], v[214:215], v[242:243]
	v_pk_fma_f32 v[94:95], v[214:215], s[30:31], v[182:183] op_sel_hi:[1,0,1]
	v_pk_add_f32 v[216:217], v[216:217], v[250:251] op_sel_hi:[1,0] neg_lo:[0,1] neg_hi:[0,1]
	v_pk_mul_f32 v[216:217], v[216:217], v[250:251] op_sel:[0,1]
	v_pk_fma_f32 v[216:217], v[136:137], v[216:217], v[244:245]
	v_pk_fma_f32 v[96:97], v[216:217], s[30:31], v[184:185] op_sel_hi:[1,0,1]
	s_mov_b32 s10, 0x80000
	v_lshl_add_u64 v[150:151], v[226:227], 0, s[10:11]
	global_load_dwordx2 v[138:139], v[228:229], off offset:1024
	global_load_dwordx2 v[246:247], v[228:229], off offset:1280
	global_load_dwordx2 v[248:249], v[228:229], off offset:1536
	global_load_dwordx2 v[250:251], v[228:229], off offset:1792
	global_load_dwordx4 v[130:133], v[230:231], off offset:0
	global_load_dwordx4 v[134:137], v[230:231], off offset:16
	global_load_dwordx4 v[238:241], v[232:233], off offset:0
	global_load_dwordx4 v[242:245], v[232:233], off offset:16
	global_load_dwordx4 v[186:189], v[150:151], off
	global_load_dwordx4 v[190:193], v[150:151], off offset:16
	v_lshl_add_u64 v[218:219], v[150:151], 0, s[4:5]
	global_load_dwordx4 v[194:197], v[218:219], off
	global_load_dwordx4 v[198:201], v[218:219], off offset:16
	v_lshl_add_u64 v[218:219], v[150:151], 0, s[6:7]
	global_load_dwordx4 v[202:205], v[218:219], off
	global_load_dwordx4 v[206:209], v[218:219], off offset:16
	v_lshl_add_u64 v[218:219], v[150:151], 0, s[8:9]
	global_load_dwordx4 v[210:213], v[218:219], off
	global_load_dwordx4 v[214:217], v[218:219], off offset:16
	ds_write2st64_b32 v153, v34, v35 offset1:2
	ds_write2st64_b32 v153, v36, v37 offset0:4 offset1:6
	ds_write2st64_b32 v252, v38, v39 offset1:2
	ds_write2st64_b32 v252, v40, v41 offset0:4 offset1:6
	ds_write2st64_b32 v153, v42, v43 offset0:32 offset1:34
	ds_write2st64_b32 v153, v44, v45 offset0:36 offset1:38
	ds_write2st64_b32 v252, v46, v47 offset0:32 offset1:34
	ds_write2st64_b32 v252, v48, v49 offset0:36 offset1:38
	ds_write2st64_b32 v153, v50, v51 offset0:64 offset1:66
	ds_write2st64_b32 v153, v52, v53 offset0:68 offset1:70
	ds_write2st64_b32 v252, v54, v55 offset0:64 offset1:66
	ds_write2st64_b32 v252, v56, v57 offset0:68 offset1:70
	ds_write2st64_b32 v153, v58, v59 offset0:96 offset1:98
	ds_write2st64_b32 v153, v60, v61 offset0:100 offset1:102
	ds_write2st64_b32 v252, v62, v63 offset0:96 offset1:98
	ds_write2st64_b32 v252, v64, v65 offset0:100 offset1:102
	s_waitcnt lgkmcnt(0)
	s_barrier
	ds_read_b128 v[154:157], v147
	ds_read_b128 v[158:161], v148
	ds_read_b128 v[162:165], v146
	ds_read_b128 v[166:169], v145
	ds_read_b128 v[170:173], v144
	ds_read_b128 v[174:177], v143
	ds_read_b128 v[178:181], v141
	ds_read_b128 v[182:185], v140
	s_waitcnt vmcnt(0) lgkmcnt(0)
	s_barrier
	v_pk_add_f32 v[186:187], v[186:187], v[138:139] op_sel_hi:[1,0] neg_lo:[0,1] neg_hi:[0,1]
	v_pk_mul_f32 v[186:187], v[186:187], v[138:139] op_sel:[0,1]
	v_pk_fma_f32 v[186:187], v[130:131], v[186:187], v[238:239]
	v_pk_fma_f32 v[34:35], v[186:187], s[30:31], v[154:155] op_sel_hi:[1,0,1]
	v_pk_add_f32 v[188:189], v[188:189], v[138:139] op_sel_hi:[1,0] neg_lo:[0,1] neg_hi:[0,1]
	v_pk_mul_f32 v[188:189], v[188:189], v[138:139] op_sel:[0,1]
	v_pk_fma_f32 v[188:189], v[132:133], v[188:189], v[240:241]
	v_pk_fma_f32 v[36:37], v[188:189], s[30:31], v[156:157] op_sel_hi:[1,0,1]
	v_pk_add_f32 v[190:191], v[190:191], v[138:139] op_sel_hi:[1,0] neg_lo:[0,1] neg_hi:[0,1]
	v_pk_mul_f32 v[190:191], v[190:191], v[138:139] op_sel:[0,1]
	v_pk_fma_f32 v[190:191], v[134:135], v[190:191], v[242:243]
	v_pk_fma_f32 v[38:39], v[190:191], s[30:31], v[158:159] op_sel_hi:[1,0,1]
	v_pk_add_f32 v[192:193], v[192:193], v[138:139] op_sel_hi:[1,0] neg_lo:[0,1] neg_hi:[0,1]
	v_pk_mul_f32 v[192:193], v[192:193], v[138:139] op_sel:[0,1]
	v_pk_fma_f32 v[192:193], v[136:137], v[192:193], v[244:245]
	v_pk_fma_f32 v[40:41], v[192:193], s[30:31], v[160:161] op_sel_hi:[1,0,1]
	v_pk_add_f32 v[194:195], v[194:195], v[246:247] op_sel_hi:[1,0] neg_lo:[0,1] neg_hi:[0,1]
	v_pk_mul_f32 v[194:195], v[194:195], v[246:247] op_sel:[0,1]
	v_pk_fma_f32 v[194:195], v[130:131], v[194:195], v[238:239]
	v_pk_fma_f32 v[42:43], v[194:195], s[30:31], v[162:163] op_sel_hi:[1,0,1]
	v_pk_add_f32 v[196:197], v[196:197], v[246:247] op_sel_hi:[1,0] neg_lo:[0,1] neg_hi:[0,1]
	v_pk_mul_f32 v[196:197], v[196:197], v[246:247] op_sel:[0,1]
	v_pk_fma_f32 v[196:197], v[132:133], v[196:197], v[240:241]
	v_pk_fma_f32 v[44:45], v[196:197], s[30:31], v[164:165] op_sel_hi:[1,0,1]
	v_pk_add_f32 v[198:199], v[198:199], v[246:247] op_sel_hi:[1,0] neg_lo:[0,1] neg_hi:[0,1]
	v_pk_mul_f32 v[198:199], v[198:199], v[246:247] op_sel:[0,1]
	v_pk_fma_f32 v[198:199], v[134:135], v[198:199], v[242:243]
	v_pk_fma_f32 v[46:47], v[198:199], s[30:31], v[166:167] op_sel_hi:[1,0,1]
	v_pk_add_f32 v[200:201], v[200:201], v[246:247] op_sel_hi:[1,0] neg_lo:[0,1] neg_hi:[0,1]
	v_pk_mul_f32 v[200:201], v[200:201], v[246:247] op_sel:[0,1]
	v_pk_fma_f32 v[200:201], v[136:137], v[200:201], v[244:245]
	v_pk_fma_f32 v[48:49], v[200:201], s[30:31], v[168:169] op_sel_hi:[1,0,1]
	v_pk_add_f32 v[202:203], v[202:203], v[248:249] op_sel_hi:[1,0] neg_lo:[0,1] neg_hi:[0,1]
	v_pk_mul_f32 v[202:203], v[202:203], v[248:249] op_sel:[0,1]
	v_pk_fma_f32 v[202:203], v[130:131], v[202:203], v[238:239]
	v_pk_fma_f32 v[50:51], v[202:203], s[30:31], v[170:171] op_sel_hi:[1,0,1]
	v_pk_add_f32 v[204:205], v[204:205], v[248:249] op_sel_hi:[1,0] neg_lo:[0,1] neg_hi:[0,1]
	v_pk_mul_f32 v[204:205], v[204:205], v[248:249] op_sel:[0,1]
	v_pk_fma_f32 v[204:205], v[132:133], v[204:205], v[240:241]
	v_pk_fma_f32 v[52:53], v[204:205], s[30:31], v[172:173] op_sel_hi:[1,0,1]
	v_pk_add_f32 v[206:207], v[206:207], v[248:249] op_sel_hi:[1,0] neg_lo:[0,1] neg_hi:[0,1]
	v_pk_mul_f32 v[206:207], v[206:207], v[248:249] op_sel:[0,1]
	v_pk_fma_f32 v[206:207], v[134:135], v[206:207], v[242:243]
	v_pk_fma_f32 v[54:55], v[206:207], s[30:31], v[174:175] op_sel_hi:[1,0,1]
	v_pk_add_f32 v[208:209], v[208:209], v[248:249] op_sel_hi:[1,0] neg_lo:[0,1] neg_hi:[0,1]
	v_pk_mul_f32 v[208:209], v[208:209], v[248:249] op_sel:[0,1]
	v_pk_fma_f32 v[208:209], v[136:137], v[208:209], v[244:245]
	v_pk_fma_f32 v[56:57], v[208:209], s[30:31], v[176:177] op_sel_hi:[1,0,1]
	v_pk_add_f32 v[210:211], v[210:211], v[250:251] op_sel_hi:[1,0] neg_lo:[0,1] neg_hi:[0,1]
	v_pk_mul_f32 v[210:211], v[210:211], v[250:251] op_sel:[0,1]
	v_pk_fma_f32 v[210:211], v[130:131], v[210:211], v[238:239]
	v_pk_fma_f32 v[58:59], v[210:211], s[30:31], v[178:179] op_sel_hi:[1,0,1]
	v_pk_add_f32 v[212:213], v[212:213], v[250:251] op_sel_hi:[1,0] neg_lo:[0,1] neg_hi:[0,1]
	v_pk_mul_f32 v[212:213], v[212:213], v[250:251] op_sel:[0,1]
	v_pk_fma_f32 v[212:213], v[132:133], v[212:213], v[240:241]
	v_pk_fma_f32 v[60:61], v[212:213], s[30:31], v[180:181] op_sel_hi:[1,0,1]
	v_pk_add_f32 v[214:215], v[214:215], v[250:251] op_sel_hi:[1,0] neg_lo:[0,1] neg_hi:[0,1]
	v_pk_mul_f32 v[214:215], v[214:215], v[250:251] op_sel:[0,1]
	v_pk_fma_f32 v[214:215], v[134:135], v[214:215], v[242:243]
	v_pk_fma_f32 v[62:63], v[214:215], s[30:31], v[182:183] op_sel_hi:[1,0,1]
	v_pk_add_f32 v[216:217], v[216:217], v[250:251] op_sel_hi:[1,0] neg_lo:[0,1] neg_hi:[0,1]
	v_pk_mul_f32 v[216:217], v[216:217], v[250:251] op_sel:[0,1]
	v_pk_fma_f32 v[216:217], v[136:137], v[216:217], v[244:245]
	v_pk_fma_f32 v[64:65], v[216:217], s[30:31], v[184:185] op_sel_hi:[1,0,1]
	s_mov_b32 s10, 0x80200
	v_lshl_add_u64 v[150:151], v[226:227], 0, s[10:11]
	global_load_dwordx2 v[138:139], v[228:229], off offset:1024
	global_load_dwordx2 v[246:247], v[228:229], off offset:1280
	global_load_dwordx2 v[248:249], v[228:229], off offset:1536
	global_load_dwordx2 v[250:251], v[228:229], off offset:1792
	global_load_dwordx4 v[130:133], v[230:231], off offset:512
	global_load_dwordx4 v[134:137], v[230:231], off offset:528
	global_load_dwordx4 v[238:241], v[232:233], off offset:512
	global_load_dwordx4 v[242:245], v[232:233], off offset:528
	global_load_dwordx4 v[186:189], v[150:151], off
	global_load_dwordx4 v[190:193], v[150:151], off offset:16
	v_lshl_add_u64 v[218:219], v[150:151], 0, s[4:5]
	global_load_dwordx4 v[194:197], v[218:219], off
	global_load_dwordx4 v[198:201], v[218:219], off offset:16
	v_lshl_add_u64 v[218:219], v[150:151], 0, s[6:7]
	global_load_dwordx4 v[202:205], v[218:219], off
	global_load_dwordx4 v[206:209], v[218:219], off offset:16
	v_lshl_add_u64 v[218:219], v[150:151], 0, s[8:9]
	global_load_dwordx4 v[210:213], v[218:219], off
	global_load_dwordx4 v[214:217], v[218:219], off offset:16
	ds_write2st64_b32 v153, v2, v3 offset1:2
	ds_write2st64_b32 v153, v4, v5 offset0:4 offset1:6
	ds_write2st64_b32 v252, v6, v7 offset1:2
	ds_write2st64_b32 v252, v8, v9 offset0:4 offset1:6
	ds_write2st64_b32 v153, v10, v11 offset0:32 offset1:34
	ds_write2st64_b32 v153, v12, v13 offset0:36 offset1:38
	ds_write2st64_b32 v252, v14, v15 offset0:32 offset1:34
	ds_write2st64_b32 v252, v16, v17 offset0:36 offset1:38
	ds_write2st64_b32 v153, v18, v19 offset0:64 offset1:66
	ds_write2st64_b32 v153, v20, v21 offset0:68 offset1:70
	ds_write2st64_b32 v252, v22, v23 offset0:64 offset1:66
	ds_write2st64_b32 v252, v24, v25 offset0:68 offset1:70
	ds_write2st64_b32 v153, v26, v27 offset0:96 offset1:98
	ds_write2st64_b32 v153, v28, v29 offset0:100 offset1:102
	ds_write2st64_b32 v252, v30, v31 offset0:96 offset1:98
	ds_write2st64_b32 v252, v32, v33 offset0:100 offset1:102
	s_waitcnt lgkmcnt(0)
	s_barrier
	ds_read_b128 v[154:157], v147
	ds_read_b128 v[158:161], v148
	ds_read_b128 v[162:165], v146
	ds_read_b128 v[166:169], v145
	ds_read_b128 v[170:173], v144
	ds_read_b128 v[174:177], v143
	ds_read_b128 v[178:181], v141
	ds_read_b128 v[182:185], v140
	s_waitcnt vmcnt(0) lgkmcnt(0)
	v_pk_add_f32 v[186:187], v[186:187], v[138:139] op_sel_hi:[1,0] neg_lo:[0,1] neg_hi:[0,1]
	v_pk_mul_f32 v[186:187], v[186:187], v[138:139] op_sel:[0,1]
	v_pk_fma_f32 v[186:187], v[130:131], v[186:187], v[238:239]
	v_pk_fma_f32 v[2:3], v[186:187], s[30:31], v[154:155] op_sel_hi:[1,0,1]
	v_pk_add_f32 v[188:189], v[188:189], v[138:139] op_sel_hi:[1,0] neg_lo:[0,1] neg_hi:[0,1]
	v_pk_mul_f32 v[188:189], v[188:189], v[138:139] op_sel:[0,1]
	v_pk_fma_f32 v[188:189], v[132:133], v[188:189], v[240:241]
	v_pk_fma_f32 v[4:5], v[188:189], s[30:31], v[156:157] op_sel_hi:[1,0,1]
	v_pk_add_f32 v[190:191], v[190:191], v[138:139] op_sel_hi:[1,0] neg_lo:[0,1] neg_hi:[0,1]
	v_pk_mul_f32 v[190:191], v[190:191], v[138:139] op_sel:[0,1]
	v_pk_fma_f32 v[190:191], v[134:135], v[190:191], v[242:243]
	v_pk_fma_f32 v[6:7], v[190:191], s[30:31], v[158:159] op_sel_hi:[1,0,1]
	v_pk_add_f32 v[192:193], v[192:193], v[138:139] op_sel_hi:[1,0] neg_lo:[0,1] neg_hi:[0,1]
	v_pk_mul_f32 v[192:193], v[192:193], v[138:139] op_sel:[0,1]
	v_pk_fma_f32 v[192:193], v[136:137], v[192:193], v[244:245]
	v_pk_fma_f32 v[8:9], v[192:193], s[30:31], v[160:161] op_sel_hi:[1,0,1]
	v_pk_add_f32 v[194:195], v[194:195], v[246:247] op_sel_hi:[1,0] neg_lo:[0,1] neg_hi:[0,1]
	v_pk_mul_f32 v[194:195], v[194:195], v[246:247] op_sel:[0,1]
	v_pk_fma_f32 v[194:195], v[130:131], v[194:195], v[238:239]
	v_pk_fma_f32 v[10:11], v[194:195], s[30:31], v[162:163] op_sel_hi:[1,0,1]
	v_pk_add_f32 v[196:197], v[196:197], v[246:247] op_sel_hi:[1,0] neg_lo:[0,1] neg_hi:[0,1]
	v_pk_mul_f32 v[196:197], v[196:197], v[246:247] op_sel:[0,1]
	v_pk_fma_f32 v[196:197], v[132:133], v[196:197], v[240:241]
	v_pk_fma_f32 v[12:13], v[196:197], s[30:31], v[164:165] op_sel_hi:[1,0,1]
	v_pk_add_f32 v[198:199], v[198:199], v[246:247] op_sel_hi:[1,0] neg_lo:[0,1] neg_hi:[0,1]
	v_pk_mul_f32 v[198:199], v[198:199], v[246:247] op_sel:[0,1]
	v_pk_fma_f32 v[198:199], v[134:135], v[198:199], v[242:243]
	v_pk_fma_f32 v[14:15], v[198:199], s[30:31], v[166:167] op_sel_hi:[1,0,1]
	v_pk_add_f32 v[200:201], v[200:201], v[246:247] op_sel_hi:[1,0] neg_lo:[0,1] neg_hi:[0,1]
	v_pk_mul_f32 v[200:201], v[200:201], v[246:247] op_sel:[0,1]
	v_pk_fma_f32 v[200:201], v[136:137], v[200:201], v[244:245]
	v_pk_fma_f32 v[16:17], v[200:201], s[30:31], v[168:169] op_sel_hi:[1,0,1]
	v_pk_add_f32 v[202:203], v[202:203], v[248:249] op_sel_hi:[1,0] neg_lo:[0,1] neg_hi:[0,1]
	v_pk_mul_f32 v[202:203], v[202:203], v[248:249] op_sel:[0,1]
	v_pk_fma_f32 v[202:203], v[130:131], v[202:203], v[238:239]
	v_pk_fma_f32 v[18:19], v[202:203], s[30:31], v[170:171] op_sel_hi:[1,0,1]
	v_pk_add_f32 v[204:205], v[204:205], v[248:249] op_sel_hi:[1,0] neg_lo:[0,1] neg_hi:[0,1]
	v_pk_mul_f32 v[204:205], v[204:205], v[248:249] op_sel:[0,1]
	v_pk_fma_f32 v[204:205], v[132:133], v[204:205], v[240:241]
	v_pk_fma_f32 v[20:21], v[204:205], s[30:31], v[172:173] op_sel_hi:[1,0,1]
	v_pk_add_f32 v[206:207], v[206:207], v[248:249] op_sel_hi:[1,0] neg_lo:[0,1] neg_hi:[0,1]
	v_pk_mul_f32 v[206:207], v[206:207], v[248:249] op_sel:[0,1]
	v_pk_fma_f32 v[206:207], v[134:135], v[206:207], v[242:243]
	v_pk_fma_f32 v[22:23], v[206:207], s[30:31], v[174:175] op_sel_hi:[1,0,1]
	v_pk_add_f32 v[208:209], v[208:209], v[248:249] op_sel_hi:[1,0] neg_lo:[0,1] neg_hi:[0,1]
	v_pk_mul_f32 v[208:209], v[208:209], v[248:249] op_sel:[0,1]
	v_pk_fma_f32 v[208:209], v[136:137], v[208:209], v[244:245]
	v_pk_fma_f32 v[24:25], v[208:209], s[30:31], v[176:177] op_sel_hi:[1,0,1]
	v_pk_add_f32 v[210:211], v[210:211], v[250:251] op_sel_hi:[1,0] neg_lo:[0,1] neg_hi:[0,1]
	v_pk_mul_f32 v[210:211], v[210:211], v[250:251] op_sel:[0,1]
	v_pk_fma_f32 v[210:211], v[130:131], v[210:211], v[238:239]
	v_pk_fma_f32 v[26:27], v[210:211], s[30:31], v[178:179] op_sel_hi:[1,0,1]
	v_pk_add_f32 v[212:213], v[212:213], v[250:251] op_sel_hi:[1,0] neg_lo:[0,1] neg_hi:[0,1]
	v_pk_mul_f32 v[212:213], v[212:213], v[250:251] op_sel:[0,1]
	v_pk_fma_f32 v[212:213], v[132:133], v[212:213], v[240:241]
	v_pk_fma_f32 v[28:29], v[212:213], s[30:31], v[180:181] op_sel_hi:[1,0,1]
	v_pk_add_f32 v[214:215], v[214:215], v[250:251] op_sel_hi:[1,0] neg_lo:[0,1] neg_hi:[0,1]
	v_pk_mul_f32 v[214:215], v[214:215], v[250:251] op_sel:[0,1]
	v_pk_fma_f32 v[214:215], v[134:135], v[214:215], v[242:243]
	v_pk_fma_f32 v[30:31], v[214:215], s[30:31], v[182:183] op_sel_hi:[1,0,1]
	v_pk_add_f32 v[216:217], v[216:217], v[250:251] op_sel_hi:[1,0] neg_lo:[0,1] neg_hi:[0,1]
	v_pk_mul_f32 v[216:217], v[216:217], v[250:251] op_sel:[0,1]
	v_pk_fma_f32 v[216:217], v[136:137], v[216:217], v[244:245]
	v_pk_fma_f32 v[32:33], v[216:217], s[30:31], v[184:185] op_sel_hi:[1,0,1]
	global_load_dwordx4 v[186:189], v222, s[56:57] offset:0
	global_load_dwordx4 v[190:193], v222, s[56:57] offset:16
	global_load_dwordx4 v[194:197], v222, s[56:57] offset:512
	global_load_dwordx4 v[198:201], v222, s[56:57] offset:528
	global_load_dwordx4 v[202:205], v222, s[58:59] offset:0
	global_load_dwordx4 v[206:209], v222, s[58:59] offset:16
	global_load_dwordx4 v[210:213], v222, s[58:59] offset:512
	global_load_dwordx4 v[214:217], v222, s[58:59] offset:528
	v_lshl_add_u64 v[184:185], s[60:61], 0, v[224:225]
	v_lshrrev_b32_e32 v183, 4, v0
	v_lshlrev_b32_e32 v183, 3, v183
	v_pk_add_f32 v[146:147], v[98:99], v[100:101]
	v_pk_add_f32 v[148:149], v[106:107], v[108:109]
	v_pk_add_f32 v[150:151], v[114:115], v[116:117]
	v_pk_add_f32 v[152:153], v[122:123], v[124:125]
	v_pk_add_f32 v[154:155], v[34:35], v[36:37]
	v_pk_add_f32 v[156:157], v[42:43], v[44:45]
	v_pk_add_f32 v[158:159], v[50:51], v[52:53]
	v_pk_add_f32 v[160:161], v[58:59], v[60:61]
	v_pk_add_f32 v[146:147], v[146:147], v[102:103]
	v_pk_add_f32 v[148:149], v[148:149], v[110:111]
	v_pk_add_f32 v[150:151], v[150:151], v[118:119]
	v_pk_add_f32 v[152:153], v[152:153], v[126:127]
	v_pk_add_f32 v[154:155], v[154:155], v[38:39]
	v_pk_add_f32 v[156:157], v[156:157], v[46:47]
	v_pk_add_f32 v[158:159], v[158:159], v[54:55]
	v_pk_add_f32 v[160:161], v[160:161], v[62:63]
	v_pk_add_f32 v[146:147], v[146:147], v[104:105]
	v_pk_add_f32 v[148:149], v[148:149], v[112:113]
	v_pk_add_f32 v[150:151], v[150:151], v[120:121]
	v_pk_add_f32 v[152:153], v[152:153], v[128:129]
	v_pk_add_f32 v[154:155], v[154:155], v[40:41]
	v_pk_add_f32 v[156:157], v[156:157], v[48:49]
	v_pk_add_f32 v[158:159], v[158:159], v[56:57]
	v_pk_add_f32 v[160:161], v[160:161], v[64:65]
	v_pk_add_f32 v[146:147], v[146:147], v[66:67]
	v_pk_add_f32 v[148:149], v[148:149], v[74:75]
	v_pk_add_f32 v[150:151], v[150:151], v[82:83]
	v_pk_add_f32 v[152:153], v[152:153], v[90:91]
	v_pk_add_f32 v[154:155], v[154:155], v[2:3]
	v_pk_add_f32 v[156:157], v[156:157], v[10:11]
	v_pk_add_f32 v[158:159], v[158:159], v[18:19]
	v_pk_add_f32 v[160:161], v[160:161], v[26:27]
	v_pk_add_f32 v[146:147], v[146:147], v[68:69]
	v_pk_add_f32 v[148:149], v[148:149], v[76:77]
	v_pk_add_f32 v[150:151], v[150:151], v[84:85]
	v_pk_add_f32 v[152:153], v[152:153], v[92:93]
	v_pk_add_f32 v[154:155], v[154:155], v[4:5]
	v_pk_add_f32 v[156:157], v[156:157], v[12:13]
	v_pk_add_f32 v[158:159], v[158:159], v[20:21]
	v_pk_add_f32 v[160:161], v[160:161], v[28:29]
	v_pk_add_f32 v[146:147], v[146:147], v[70:71]
	v_pk_add_f32 v[148:149], v[148:149], v[78:79]
	v_pk_add_f32 v[150:151], v[150:151], v[86:87]
	v_pk_add_f32 v[152:153], v[152:153], v[94:95]
	v_pk_add_f32 v[154:155], v[154:155], v[6:7]
	v_pk_add_f32 v[156:157], v[156:157], v[14:15]
	v_pk_add_f32 v[158:159], v[158:159], v[22:23]
	v_pk_add_f32 v[160:161], v[160:161], v[30:31]
	v_pk_add_f32 v[146:147], v[146:147], v[72:73]
	v_pk_add_f32 v[148:149], v[148:149], v[80:81]
	v_pk_add_f32 v[150:151], v[150:151], v[88:89]
	v_pk_add_f32 v[152:153], v[152:153], v[96:97]
	v_pk_add_f32 v[154:155], v[154:155], v[8:9]
	v_pk_add_f32 v[156:157], v[156:157], v[16:17]
	v_pk_add_f32 v[158:159], v[158:159], v[24:25]
	v_pk_add_f32 v[160:161], v[160:161], v[32:33]
	v_add_f32_e32 v130, v146, v147
	v_add_f32_e32 v132, v148, v149
	v_add_f32_e32 v134, v150, v151
	v_add_f32_e32 v136, v152, v153
	v_add_f32_e32 v138, v154, v155
	v_add_f32_e32 v140, v156, v157
	v_add_f32_e32 v142, v158, v159
	v_add_f32_e32 v144, v160, v161
	v_add_f32_dpp v130, v130, v130 quad_perm:[1,0,3,2] row_mask:0xf bank_mask:0xf
	v_add_f32_dpp v132, v132, v132 quad_perm:[1,0,3,2] row_mask:0xf bank_mask:0xf
	v_add_f32_dpp v134, v134, v134 quad_perm:[1,0,3,2] row_mask:0xf bank_mask:0xf
	v_add_f32_dpp v136, v136, v136 quad_perm:[1,0,3,2] row_mask:0xf bank_mask:0xf
	v_add_f32_dpp v138, v138, v138 quad_perm:[1,0,3,2] row_mask:0xf bank_mask:0xf
	v_add_f32_dpp v140, v140, v140 quad_perm:[1,0,3,2] row_mask:0xf bank_mask:0xf
	v_add_f32_dpp v142, v142, v142 quad_perm:[1,0,3,2] row_mask:0xf bank_mask:0xf
	v_add_f32_dpp v144, v144, v144 quad_perm:[1,0,3,2] row_mask:0xf bank_mask:0xf
	v_add_f32_dpp v130, v130, v130 quad_perm:[2,3,0,1] row_mask:0xf bank_mask:0xf
	v_add_f32_dpp v132, v132, v132 quad_perm:[2,3,0,1] row_mask:0xf bank_mask:0xf
	v_add_f32_dpp v134, v134, v134 quad_perm:[2,3,0,1] row_mask:0xf bank_mask:0xf
	v_add_f32_dpp v136, v136, v136 quad_perm:[2,3,0,1] row_mask:0xf bank_mask:0xf
	v_add_f32_dpp v138, v138, v138 quad_perm:[2,3,0,1] row_mask:0xf bank_mask:0xf
	v_add_f32_dpp v140, v140, v140 quad_perm:[2,3,0,1] row_mask:0xf bank_mask:0xf
	v_add_f32_dpp v142, v142, v142 quad_perm:[2,3,0,1] row_mask:0xf bank_mask:0xf
	v_add_f32_dpp v144, v144, v144 quad_perm:[2,3,0,1] row_mask:0xf bank_mask:0xf
	v_add_f32_dpp v130, v130, v130 row_half_mirror row_mask:0xf bank_mask:0xf
	v_add_f32_dpp v132, v132, v132 row_half_mirror row_mask:0xf bank_mask:0xf
	v_add_f32_dpp v134, v134, v134 row_half_mirror row_mask:0xf bank_mask:0xf
	v_add_f32_dpp v136, v136, v136 row_half_mirror row_mask:0xf bank_mask:0xf
	v_add_f32_dpp v138, v138, v138 row_half_mirror row_mask:0xf bank_mask:0xf
	v_add_f32_dpp v140, v140, v140 row_half_mirror row_mask:0xf bank_mask:0xf
	v_add_f32_dpp v142, v142, v142 row_half_mirror row_mask:0xf bank_mask:0xf
	v_add_f32_dpp v144, v144, v144 row_half_mirror row_mask:0xf bank_mask:0xf
	v_add_f32_dpp v130, v130, v130 row_mirror row_mask:0xf bank_mask:0xf
	v_add_f32_dpp v132, v132, v132 row_mirror row_mask:0xf bank_mask:0xf
	v_add_f32_dpp v134, v134, v134 row_mirror row_mask:0xf bank_mask:0xf
	v_add_f32_dpp v136, v136, v136 row_mirror row_mask:0xf bank_mask:0xf
	v_add_f32_dpp v138, v138, v138 row_mirror row_mask:0xf bank_mask:0xf
	v_add_f32_dpp v140, v140, v140 row_mirror row_mask:0xf bank_mask:0xf
	v_add_f32_dpp v142, v142, v142 row_mirror row_mask:0xf bank_mask:0xf
	v_add_f32_dpp v144, v144, v144 row_mirror row_mask:0xf bank_mask:0xf
	v_mul_f32_e32 v130, 0x3b800000, v130
	v_mul_f32_e32 v132, 0x3b800000, v132
	v_mul_f32_e32 v134, 0x3b800000, v134
	v_mul_f32_e32 v136, 0x3b800000, v136
	v_mul_f32_e32 v138, 0x3b800000, v138
	v_mul_f32_e32 v140, 0x3b800000, v140
	v_mul_f32_e32 v142, 0x3b800000, v142
	v_mul_f32_e32 v144, 0x3b800000, v144
	v_pk_add_f32 v[162:163], v[98:99], v[130:131] op_sel_hi:[1,0] neg_lo:[0,1] neg_hi:[0,1]
	v_pk_mul_f32 v[164:165], v[162:163], v[162:163]
	v_pk_add_f32 v[180:181], v[106:107], v[132:133] op_sel_hi:[1,0] neg_lo:[0,1] neg_hi:[0,1]
	v_pk_mul_f32 v[166:167], v[180:181], v[180:181]
	v_pk_add_f32 v[162:163], v[114:115], v[134:135] op_sel_hi:[1,0] neg_lo:[0,1] neg_hi:[0,1]
	v_pk_mul_f32 v[168:169], v[162:163], v[162:163]
	v_pk_add_f32 v[180:181], v[122:123], v[136:137] op_sel_hi:[1,0] neg_lo:[0,1] neg_hi:[0,1]
	v_pk_mul_f32 v[170:171], v[180:181], v[180:181]
	v_pk_add_f32 v[162:163], v[34:35], v[138:139] op_sel_hi:[1,0] neg_lo:[0,1] neg_hi:[0,1]
	v_pk_mul_f32 v[172:173], v[162:163], v[162:163]
	v_pk_add_f32 v[180:181], v[42:43], v[140:141] op_sel_hi:[1,0] neg_lo:[0,1] neg_hi:[0,1]
	v_pk_mul_f32 v[174:175], v[180:181], v[180:181]
	v_pk_add_f32 v[162:163], v[50:51], v[142:143] op_sel_hi:[1,0] neg_lo:[0,1] neg_hi:[0,1]
	v_pk_mul_f32 v[176:177], v[162:163], v[162:163]
	v_pk_add_f32 v[180:181], v[58:59], v[144:145] op_sel_hi:[1,0] neg_lo:[0,1] neg_hi:[0,1]
	v_pk_mul_f32 v[178:179], v[180:181], v[180:181]
	v_pk_add_f32 v[162:163], v[100:101], v[130:131] op_sel_hi:[1,0] neg_lo:[0,1] neg_hi:[0,1]
	v_pk_fma_f32 v[164:165], v[162:163], v[162:163], v[164:165]
	v_pk_add_f32 v[180:181], v[108:109], v[132:133] op_sel_hi:[1,0] neg_lo:[0,1] neg_hi:[0,1]
	v_pk_fma_f32 v[166:167], v[180:181], v[180:181], v[166:167]
	v_pk_add_f32 v[162:163], v[116:117], v[134:135] op_sel_hi:[1,0] neg_lo:[0,1] neg_hi:[0,1]
	v_pk_fma_f32 v[168:169], v[162:163], v[162:163], v[168:169]
	v_pk_add_f32 v[180:181], v[124:125], v[136:137] op_sel_hi:[1,0] neg_lo:[0,1] neg_hi:[0,1]
	v_pk_fma_f32 v[170:171], v[180:181], v[180:181], v[170:171]
	v_pk_add_f32 v[162:163], v[36:37], v[138:139] op_sel_hi:[1,0] neg_lo:[0,1] neg_hi:[0,1]
	v_pk_fma_f32 v[172:173], v[162:163], v[162:163], v[172:173]
	v_pk_add_f32 v[180:181], v[44:45], v[140:141] op_sel_hi:[1,0] neg_lo:[0,1] neg_hi:[0,1]
	v_pk_fma_f32 v[174:175], v[180:181], v[180:181], v[174:175]
	v_pk_add_f32 v[162:163], v[52:53], v[142:143] op_sel_hi:[1,0] neg_lo:[0,1] neg_hi:[0,1]
	v_pk_fma_f32 v[176:177], v[162:163], v[162:163], v[176:177]
	v_pk_add_f32 v[180:181], v[60:61], v[144:145] op_sel_hi:[1,0] neg_lo:[0,1] neg_hi:[0,1]
	v_pk_fma_f32 v[178:179], v[180:181], v[180:181], v[178:179]
	v_pk_add_f32 v[162:163], v[102:103], v[130:131] op_sel_hi:[1,0] neg_lo:[0,1] neg_hi:[0,1]
	v_pk_fma_f32 v[164:165], v[162:163], v[162:163], v[164:165]
	v_pk_add_f32 v[180:181], v[110:111], v[132:133] op_sel_hi:[1,0] neg_lo:[0,1] neg_hi:[0,1]
	v_pk_fma_f32 v[166:167], v[180:181], v[180:181], v[166:167]
	v_pk_add_f32 v[162:163], v[118:119], v[134:135] op_sel_hi:[1,0] neg_lo:[0,1] neg_hi:[0,1]
	v_pk_fma_f32 v[168:169], v[162:163], v[162:163], v[168:169]
	v_pk_add_f32 v[180:181], v[126:127], v[136:137] op_sel_hi:[1,0] neg_lo:[0,1] neg_hi:[0,1]
	v_pk_fma_f32 v[170:171], v[180:181], v[180:181], v[170:171]
	v_pk_add_f32 v[162:163], v[38:39], v[138:139] op_sel_hi:[1,0] neg_lo:[0,1] neg_hi:[0,1]
	v_pk_fma_f32 v[172:173], v[162:163], v[162:163], v[172:173]
	v_pk_add_f32 v[180:181], v[46:47], v[140:141] op_sel_hi:[1,0] neg_lo:[0,1] neg_hi:[0,1]
	v_pk_fma_f32 v[174:175], v[180:181], v[180:181], v[174:175]
	v_pk_add_f32 v[162:163], v[54:55], v[142:143] op_sel_hi:[1,0] neg_lo:[0,1] neg_hi:[0,1]
	v_pk_fma_f32 v[176:177], v[162:163], v[162:163], v[176:177]
	v_pk_add_f32 v[180:181], v[62:63], v[144:145] op_sel_hi:[1,0] neg_lo:[0,1] neg_hi:[0,1]
	v_pk_fma_f32 v[178:179], v[180:181], v[180:181], v[178:179]
	v_pk_add_f32 v[162:163], v[104:105], v[130:131] op_sel_hi:[1,0] neg_lo:[0,1] neg_hi:[0,1]
	v_pk_fma_f32 v[164:165], v[162:163], v[162:163], v[164:165]
	v_pk_add_f32 v[180:181], v[112:113], v[132:133] op_sel_hi:[1,0] neg_lo:[0,1] neg_hi:[0,1]
	v_pk_fma_f32 v[166:167], v[180:181], v[180:181], v[166:167]
	v_pk_add_f32 v[162:163], v[120:121], v[134:135] op_sel_hi:[1,0] neg_lo:[0,1] neg_hi:[0,1]
	v_pk_fma_f32 v[168:169], v[162:163], v[162:163], v[168:169]
	v_pk_add_f32 v[180:181], v[128:129], v[136:137] op_sel_hi:[1,0] neg_lo:[0,1] neg_hi:[0,1]
	v_pk_fma_f32 v[170:171], v[180:181], v[180:181], v[170:171]
	v_pk_add_f32 v[162:163], v[40:41], v[138:139] op_sel_hi:[1,0] neg_lo:[0,1] neg_hi:[0,1]
	v_pk_fma_f32 v[172:173], v[162:163], v[162:163], v[172:173]
	v_pk_add_f32 v[180:181], v[48:49], v[140:141] op_sel_hi:[1,0] neg_lo:[0,1] neg_hi:[0,1]
	v_pk_fma_f32 v[174:175], v[180:181], v[180:181], v[174:175]
	v_pk_add_f32 v[162:163], v[56:57], v[142:143] op_sel_hi:[1,0] neg_lo:[0,1] neg_hi:[0,1]
	v_pk_fma_f32 v[176:177], v[162:163], v[162:163], v[176:177]
	v_pk_add_f32 v[180:181], v[64:65], v[144:145] op_sel_hi:[1,0] neg_lo:[0,1] neg_hi:[0,1]
	v_pk_fma_f32 v[178:179], v[180:181], v[180:181], v[178:179]
	v_pk_add_f32 v[162:163], v[66:67], v[130:131] op_sel_hi:[1,0] neg_lo:[0,1] neg_hi:[0,1]
	v_pk_fma_f32 v[164:165], v[162:163], v[162:163], v[164:165]
	v_pk_add_f32 v[180:181], v[74:75], v[132:133] op_sel_hi:[1,0] neg_lo:[0,1] neg_hi:[0,1]
	v_pk_fma_f32 v[166:167], v[180:181], v[180:181], v[166:167]
	v_pk_add_f32 v[162:163], v[82:83], v[134:135] op_sel_hi:[1,0] neg_lo:[0,1] neg_hi:[0,1]
	v_pk_fma_f32 v[168:169], v[162:163], v[162:163], v[168:169]
	v_pk_add_f32 v[180:181], v[90:91], v[136:137] op_sel_hi:[1,0] neg_lo:[0,1] neg_hi:[0,1]
	v_pk_fma_f32 v[170:171], v[180:181], v[180:181], v[170:171]
	v_pk_add_f32 v[162:163], v[2:3], v[138:139] op_sel_hi:[1,0] neg_lo:[0,1] neg_hi:[0,1]
	v_pk_fma_f32 v[172:173], v[162:163], v[162:163], v[172:173]
	v_pk_add_f32 v[180:181], v[10:11], v[140:141] op_sel_hi:[1,0] neg_lo:[0,1] neg_hi:[0,1]
	v_pk_fma_f32 v[174:175], v[180:181], v[180:181], v[174:175]
	v_pk_add_f32 v[162:163], v[18:19], v[142:143] op_sel_hi:[1,0] neg_lo:[0,1] neg_hi:[0,1]
	v_pk_fma_f32 v[176:177], v[162:163], v[162:163], v[176:177]
	v_pk_add_f32 v[180:181], v[26:27], v[144:145] op_sel_hi:[1,0] neg_lo:[0,1] neg_hi:[0,1]
	v_pk_fma_f32 v[178:179], v[180:181], v[180:181], v[178:179]
	v_pk_add_f32 v[162:163], v[68:69], v[130:131] op_sel_hi:[1,0] neg_lo:[0,1] neg_hi:[0,1]
	v_pk_fma_f32 v[164:165], v[162:163], v[162:163], v[164:165]
	v_pk_add_f32 v[180:181], v[76:77], v[132:133] op_sel_hi:[1,0] neg_lo:[0,1] neg_hi:[0,1]
	v_pk_fma_f32 v[166:167], v[180:181], v[180:181], v[166:167]
	v_pk_add_f32 v[162:163], v[84:85], v[134:135] op_sel_hi:[1,0] neg_lo:[0,1] neg_hi:[0,1]
	v_pk_fma_f32 v[168:169], v[162:163], v[162:163], v[168:169]
	v_pk_add_f32 v[180:181], v[92:93], v[136:137] op_sel_hi:[1,0] neg_lo:[0,1] neg_hi:[0,1]
	v_pk_fma_f32 v[170:171], v[180:181], v[180:181], v[170:171]
	v_pk_add_f32 v[162:163], v[4:5], v[138:139] op_sel_hi:[1,0] neg_lo:[0,1] neg_hi:[0,1]
	v_pk_fma_f32 v[172:173], v[162:163], v[162:163], v[172:173]
	v_pk_add_f32 v[180:181], v[12:13], v[140:141] op_sel_hi:[1,0] neg_lo:[0,1] neg_hi:[0,1]
	v_pk_fma_f32 v[174:175], v[180:181], v[180:181], v[174:175]
	v_pk_add_f32 v[162:163], v[20:21], v[142:143] op_sel_hi:[1,0] neg_lo:[0,1] neg_hi:[0,1]
	v_pk_fma_f32 v[176:177], v[162:163], v[162:163], v[176:177]
	v_pk_add_f32 v[180:181], v[28:29], v[144:145] op_sel_hi:[1,0] neg_lo:[0,1] neg_hi:[0,1]
	v_pk_fma_f32 v[178:179], v[180:181], v[180:181], v[178:179]
	v_pk_add_f32 v[162:163], v[70:71], v[130:131] op_sel_hi:[1,0] neg_lo:[0,1] neg_hi:[0,1]
	v_pk_fma_f32 v[164:165], v[162:163], v[162:163], v[164:165]
	v_pk_add_f32 v[180:181], v[78:79], v[132:133] op_sel_hi:[1,0] neg_lo:[0,1] neg_hi:[0,1]
	v_pk_fma_f32 v[166:167], v[180:181], v[180:181], v[166:167]
	v_pk_add_f32 v[162:163], v[86:87], v[134:135] op_sel_hi:[1,0] neg_lo:[0,1] neg_hi:[0,1]
	v_pk_fma_f32 v[168:169], v[162:163], v[162:163], v[168:169]
	v_pk_add_f32 v[180:181], v[94:95], v[136:137] op_sel_hi:[1,0] neg_lo:[0,1] neg_hi:[0,1]
	v_pk_fma_f32 v[170:171], v[180:181], v[180:181], v[170:171]
	v_pk_add_f32 v[162:163], v[6:7], v[138:139] op_sel_hi:[1,0] neg_lo:[0,1] neg_hi:[0,1]
	v_pk_fma_f32 v[172:173], v[162:163], v[162:163], v[172:173]
	v_pk_add_f32 v[180:181], v[14:15], v[140:141] op_sel_hi:[1,0] neg_lo:[0,1] neg_hi:[0,1]
	v_pk_fma_f32 v[174:175], v[180:181], v[180:181], v[174:175]
	v_pk_add_f32 v[162:163], v[22:23], v[142:143] op_sel_hi:[1,0] neg_lo:[0,1] neg_hi:[0,1]
	v_pk_fma_f32 v[176:177], v[162:163], v[162:163], v[176:177]
	v_pk_add_f32 v[180:181], v[30:31], v[144:145] op_sel_hi:[1,0] neg_lo:[0,1] neg_hi:[0,1]
	v_pk_fma_f32 v[178:179], v[180:181], v[180:181], v[178:179]
	v_pk_add_f32 v[162:163], v[72:73], v[130:131] op_sel_hi:[1,0] neg_lo:[0,1] neg_hi:[0,1]
	v_pk_fma_f32 v[164:165], v[162:163], v[162:163], v[164:165]
	v_pk_add_f32 v[180:181], v[80:81], v[132:133] op_sel_hi:[1,0] neg_lo:[0,1] neg_hi:[0,1]
	v_pk_fma_f32 v[166:167], v[180:181], v[180:181], v[166:167]
	v_pk_add_f32 v[162:163], v[88:89], v[134:135] op_sel_hi:[1,0] neg_lo:[0,1] neg_hi:[0,1]
	v_pk_fma_f32 v[168:169], v[162:163], v[162:163], v[168:169]
	v_pk_add_f32 v[180:181], v[96:97], v[136:137] op_sel_hi:[1,0] neg_lo:[0,1] neg_hi:[0,1]
	v_pk_fma_f32 v[170:171], v[180:181], v[180:181], v[170:171]
	v_pk_add_f32 v[162:163], v[8:9], v[138:139] op_sel_hi:[1,0] neg_lo:[0,1] neg_hi:[0,1]
	v_pk_fma_f32 v[172:173], v[162:163], v[162:163], v[172:173]
	v_pk_add_f32 v[180:181], v[16:17], v[140:141] op_sel_hi:[1,0] neg_lo:[0,1] neg_hi:[0,1]
	v_pk_fma_f32 v[174:175], v[180:181], v[180:181], v[174:175]
	v_pk_add_f32 v[162:163], v[24:25], v[142:143] op_sel_hi:[1,0] neg_lo:[0,1] neg_hi:[0,1]
	v_pk_fma_f32 v[176:177], v[162:163], v[162:163], v[176:177]
	v_pk_add_f32 v[180:181], v[32:33], v[144:145] op_sel_hi:[1,0] neg_lo:[0,1] neg_hi:[0,1]
	v_pk_fma_f32 v[178:179], v[180:181], v[180:181], v[178:179]
	v_add_f32_e32 v131, v164, v165
	v_add_f32_e32 v133, v166, v167
	v_add_f32_e32 v135, v168, v169
	v_add_f32_e32 v137, v170, v171
	v_add_f32_e32 v139, v172, v173
	v_add_f32_e32 v141, v174, v175
	v_add_f32_e32 v143, v176, v177
	v_add_f32_e32 v145, v178, v179
	v_add_f32_dpp v131, v131, v131 quad_perm:[1,0,3,2] row_mask:0xf bank_mask:0xf
	v_add_f32_dpp v133, v133, v133 quad_perm:[1,0,3,2] row_mask:0xf bank_mask:0xf
	v_add_f32_dpp v135, v135, v135 quad_perm:[1,0,3,2] row_mask:0xf bank_mask:0xf
	v_add_f32_dpp v137, v137, v137 quad_perm:[1,0,3,2] row_mask:0xf bank_mask:0xf
	v_add_f32_dpp v139, v139, v139 quad_perm:[1,0,3,2] row_mask:0xf bank_mask:0xf
	v_add_f32_dpp v141, v141, v141 quad_perm:[1,0,3,2] row_mask:0xf bank_mask:0xf
	v_add_f32_dpp v143, v143, v143 quad_perm:[1,0,3,2] row_mask:0xf bank_mask:0xf
	v_add_f32_dpp v145, v145, v145 quad_perm:[1,0,3,2] row_mask:0xf bank_mask:0xf
	v_add_f32_dpp v131, v131, v131 quad_perm:[2,3,0,1] row_mask:0xf bank_mask:0xf
	v_add_f32_dpp v133, v133, v133 quad_perm:[2,3,0,1] row_mask:0xf bank_mask:0xf
	v_add_f32_dpp v135, v135, v135 quad_perm:[2,3,0,1] row_mask:0xf bank_mask:0xf
	v_add_f32_dpp v137, v137, v137 quad_perm:[2,3,0,1] row_mask:0xf bank_mask:0xf
	v_add_f32_dpp v139, v139, v139 quad_perm:[2,3,0,1] row_mask:0xf bank_mask:0xf
	v_add_f32_dpp v141, v141, v141 quad_perm:[2,3,0,1] row_mask:0xf bank_mask:0xf
	v_add_f32_dpp v143, v143, v143 quad_perm:[2,3,0,1] row_mask:0xf bank_mask:0xf
	v_add_f32_dpp v145, v145, v145 quad_perm:[2,3,0,1] row_mask:0xf bank_mask:0xf
	v_add_f32_dpp v131, v131, v131 row_half_mirror row_mask:0xf bank_mask:0xf
	v_add_f32_dpp v133, v133, v133 row_half_mirror row_mask:0xf bank_mask:0xf
	v_add_f32_dpp v135, v135, v135 row_half_mirror row_mask:0xf bank_mask:0xf
	v_add_f32_dpp v137, v137, v137 row_half_mirror row_mask:0xf bank_mask:0xf
	v_add_f32_dpp v139, v139, v139 row_half_mirror row_mask:0xf bank_mask:0xf
	v_add_f32_dpp v141, v141, v141 row_half_mirror row_mask:0xf bank_mask:0xf
	v_add_f32_dpp v143, v143, v143 row_half_mirror row_mask:0xf bank_mask:0xf
	v_add_f32_dpp v145, v145, v145 row_half_mirror row_mask:0xf bank_mask:0xf
	v_add_f32_dpp v131, v131, v131 row_mirror row_mask:0xf bank_mask:0xf
	v_add_f32_dpp v133, v133, v133 row_mirror row_mask:0xf bank_mask:0xf
	v_add_f32_dpp v135, v135, v135 row_mirror row_mask:0xf bank_mask:0xf
	v_add_f32_dpp v137, v137, v137 row_mirror row_mask:0xf bank_mask:0xf
	v_add_f32_dpp v139, v139, v139 row_mirror row_mask:0xf bank_mask:0xf
	v_add_f32_dpp v141, v141, v141 row_mirror row_mask:0xf bank_mask:0xf
	v_add_f32_dpp v143, v143, v143 row_mirror row_mask:0xf bank_mask:0xf
	v_add_f32_dpp v145, v145, v145 row_mirror row_mask:0xf bank_mask:0xf
	s_lshr_b32 s10, s49, 8
	s_lshl_b32 s10, s10, 13
	s_add_u32 s18, s62, 0xf100000
	s_addc_u32 s19, s63, 0
	s_add_u32 s18, s18, s10
	s_addc_u32 s19, s19, 0
	s_lshr_b32 s11, s36, 8
	s_lshl_b32 s11, s11, 11
	s_add_u32 s12, s18, s11
	s_addc_u32 s13, s19, 0
	s_add_u32 s20, s18, 0x1000
	s_addc_u32 s21, s19, 0
	s_mov_b32 exec_lo, 0x10001
	s_mov_b32 exec_hi, 0x10001
	global_store_dwordx2 v183, v[130:131], s[12:13] offset:0 sc1
	global_store_dwordx2 v183, v[132:133], s[12:13] offset:256 sc1
	global_store_dwordx2 v183, v[134:135], s[12:13] offset:512 sc1
	global_store_dwordx2 v183, v[136:137], s[12:13] offset:768 sc1
	global_store_dwordx2 v183, v[138:139], s[12:13] offset:1024 sc1
	global_store_dwordx2 v183, v[140:141], s[12:13] offset:1280 sc1
	global_store_dwordx2 v183, v[142:143], s[12:13] offset:1536 sc1
	global_store_dwordx2 v183, v[144:145], s[12:13] offset:1792 sc1
	s_mov_b64 exec, -1
	s_waitcnt vmcnt(0)
	s_barrier
	v_readfirstlane_b32 s14, v0
	s_nop 3
	s_lshr_b32 s14, s14, 6
	s_cmp_lg_u32 s14, 0
	s_cbranch_scc1 .Lp17_wait_done
	s_lshr_b32 s15, s49, 8
	s_lshl_b32 s15, s15, 2
	s_add_u32 s16, s62, 0xf71a000
	s_addc_u32 s17, s63, 0
	s_add_u32 s16, s16, s15
	s_addc_u32 s17, s17, 0
	v_mov_b32_e32 v162, 0
	v_mov_b32_e32 v163, 1
	s_mov_b64 exec, 1
	global_atomic_add v162, v163, s[16:17]
	s_mov_b32 s15, 0
.Lp17_poll:
	global_load_dword v164, v162, s[16:17] sc1
	s_waitcnt vmcnt(0)
	v_readfirstlane_b32 s14, v164
	s_nop 3
	s_cmp_ge_u32 s14, 4
	s_cbranch_scc1 .Lp17_polled
	s_sleep 1
	s_add_i32 s15, s15, 1
	s_cmp_lt_u32 s15, 0x4000
	s_cbranch_scc1 .Lp17_poll
.Lp17_polled:
	s_mov_b64 exec, -1
.Lp17_wait_done:
	s_barrier
	global_load_dwordx2 v[146:147], v183, s[18:19] offset:0 sc1
	global_load_dwordx2 v[148:149], v183, s[18:19] offset:2048 sc1
	global_load_dwordx2 v[150:151], v183, s[20:21] offset:0 sc1
	global_load_dwordx2 v[152:153], v183, s[20:21] offset:2048 sc1
	global_load_dwordx2 v[154:155], v183, s[18:19] offset:256 sc1
	global_load_dwordx2 v[156:157], v183, s[18:19] offset:2304 sc1
	global_load_dwordx2 v[158:159], v183, s[20:21] offset:256 sc1
	global_load_dwordx2 v[160:161], v183, s[20:21] offset:2304 sc1
	global_load_dwordx2 v[162:163], v183, s[18:19] offset:512 sc1
	global_load_dwordx2 v[164:165], v183, s[18:19] offset:2560 sc1
	global_load_dwordx2 v[166:167], v183, s[20:21] offset:512 sc1
	global_load_dwordx2 v[168:169], v183, s[20:21] offset:2560 sc1
	global_load_dwordx2 v[170:171], v183, s[18:19] offset:768 sc1
	global_load_dwordx2 v[172:173], v183, s[18:19] offset:2816 sc1
	global_load_dwordx2 v[174:175], v183, s[20:21] offset:768 sc1
	global_load_dwordx2 v[176:177], v183, s[20:21] offset:2816 sc1
	global_load_dwordx2 v[178:179], v183, s[18:19] offset:1024 sc1
	global_load_dwordx2 v[218:219], v183, s[18:19] offset:3072 sc1
	global_load_dwordx2 v[220:221], v183, s[20:21] offset:1024 sc1
	global_load_dwordx2 v[222:223], v183, s[20:21] offset:3072 sc1
	global_load_dwordx2 v[224:225], v183, s[18:19] offset:1280 sc1
	global_load_dwordx2 v[226:227], v183, s[18:19] offset:3328 sc1
	global_load_dwordx2 v[228:229], v183, s[20:21] offset:1280 sc1
	global_load_dwordx2 v[230:231], v183, s[20:21] offset:3328 sc1
	global_load_dwordx2 v[232:233], v183, s[18:19] offset:1536 sc1
	global_load_dwordx2 v[234:235], v183, s[18:19] offset:3584 sc1
	global_load_dwordx2 v[236:237], v183, s[20:21] offset:1536 sc1
	global_load_dwordx2 v[238:239], v183, s[20:21] offset:3584 sc1
	global_load_dwordx2 v[240:241], v183, s[18:19] offset:1792 sc1
	global_load_dwordx2 v[242:243], v183, s[18:19] offset:3840 sc1
	global_load_dwordx2 v[244:245], v183, s[20:21] offset:1792 sc1
	global_load_dwordx2 v[246:247], v183, s[20:21] offset:3840 sc1
	v_mov_b32_e32 v1, 0x3727c5ac
	s_waitcnt vmcnt(0)
	v_add_f32_e32 v130, v146, v148
	v_add_f32_e32 v132, v154, v156
	v_add_f32_e32 v134, v162, v164
	v_add_f32_e32 v136, v170, v172
	v_add_f32_e32 v138, v178, v218
	v_add_f32_e32 v140, v224, v226
	v_add_f32_e32 v142, v232, v234
	v_add_f32_e32 v144, v240, v242
	v_add_f32_e32 v248, v150, v152
	v_add_f32_e32 v249, v158, v160
	v_add_f32_e32 v250, v166, v168
	v_add_f32_e32 v251, v174, v176
	v_add_f32_e32 v180, v220, v222
	v_add_f32_e32 v181, v228, v230
	v_add_f32_e32 v182, v236, v238
	v_add_f32_e32 v252, v244, v246
	v_add_f32_e32 v130, v130, v248
	v_add_f32_e32 v132, v132, v249
	v_add_f32_e32 v134, v134, v250
	v_add_f32_e32 v136, v136, v251
	v_add_f32_e32 v138, v138, v180
	v_add_f32_e32 v140, v140, v181
	v_add_f32_e32 v142, v142, v182
	v_add_f32_e32 v144, v144, v252
	v_mul_f32_e32 v130, 0x3e800000, v130
	v_mul_f32_e32 v132, 0x3e800000, v132
	v_mul_f32_e32 v134, 0x3e800000, v134
	v_mul_f32_e32 v136, 0x3e800000, v136
	v_mul_f32_e32 v138, 0x3e800000, v138
	v_mul_f32_e32 v140, 0x3e800000, v140
	v_mul_f32_e32 v142, 0x3e800000, v142
	v_mul_f32_e32 v144, 0x3e800000, v144
	v_sub_f32_e32 v146, v146, v130
	v_sub_f32_e32 v154, v154, v132
	v_sub_f32_e32 v162, v162, v134
	v_sub_f32_e32 v170, v170, v136
	v_sub_f32_e32 v178, v178, v138
	v_sub_f32_e32 v224, v224, v140
	v_sub_f32_e32 v232, v232, v142
	v_sub_f32_e32 v240, v240, v144
	v_sub_f32_e32 v148, v148, v130
	v_sub_f32_e32 v156, v156, v132
	v_sub_f32_e32 v164, v164, v134
	v_sub_f32_e32 v172, v172, v136
	v_sub_f32_e32 v218, v218, v138
	v_sub_f32_e32 v226, v226, v140
	v_sub_f32_e32 v234, v234, v142
	v_sub_f32_e32 v242, v242, v144
	v_sub_f32_e32 v150, v150, v130
	v_sub_f32_e32 v158, v158, v132
	v_sub_f32_e32 v166, v166, v134
	v_sub_f32_e32 v174, v174, v136
	v_sub_f32_e32 v220, v220, v138
	v_sub_f32_e32 v228, v228, v140
	v_sub_f32_e32 v236, v236, v142
	v_sub_f32_e32 v244, v244, v144
	v_sub_f32_e32 v152, v152, v130
	v_sub_f32_e32 v160, v160, v132
	v_sub_f32_e32 v168, v168, v134
	v_sub_f32_e32 v176, v176, v136
	v_sub_f32_e32 v222, v222, v138
	v_sub_f32_e32 v230, v230, v140
	v_sub_f32_e32 v238, v238, v142
	v_sub_f32_e32 v246, v246, v144
	v_mul_f32_e32 v248, v146, v146
	v_mul_f32_e32 v249, v154, v154
	v_mul_f32_e32 v250, v162, v162
	v_mul_f32_e32 v251, v170, v170
	v_mul_f32_e32 v180, v178, v178
	v_mul_f32_e32 v181, v224, v224
	v_mul_f32_e32 v182, v232, v232
	v_mul_f32_e32 v252, v240, v240
	v_fmac_f32_e32 v248, v148, v148
	v_fmac_f32_e32 v249, v156, v156
	v_fmac_f32_e32 v250, v164, v164
	v_fmac_f32_e32 v251, v172, v172
	v_fmac_f32_e32 v180, v218, v218
	v_fmac_f32_e32 v181, v226, v226
	v_fmac_f32_e32 v182, v234, v234
	v_fmac_f32_e32 v252, v242, v242
	v_fmac_f32_e32 v248, v150, v150
	v_fmac_f32_e32 v249, v158, v158
	v_fmac_f32_e32 v250, v166, v166
	v_fmac_f32_e32 v251, v174, v174
	v_fmac_f32_e32 v180, v220, v220
	v_fmac_f32_e32 v181, v228, v228
	v_fmac_f32_e32 v182, v236, v236
	v_fmac_f32_e32 v252, v244, v244
	v_fmac_f32_e32 v248, v152, v152
	v_fmac_f32_e32 v249, v160, v160
	v_fmac_f32_e32 v250, v168, v168
	v_fmac_f32_e32 v251, v176, v176
	v_fmac_f32_e32 v180, v222, v222
	v_fmac_f32_e32 v181, v230, v230
	v_fmac_f32_e32 v182, v238, v238
	v_fmac_f32_e32 v252, v246, v246
	v_add_f32_e32 v147, v147, v149
	v_add_f32_e32 v155, v155, v157
	v_add_f32_e32 v163, v163, v165
	v_add_f32_e32 v171, v171, v173
	v_add_f32_e32 v179, v179, v219
	v_add_f32_e32 v225, v225, v227
	v_add_f32_e32 v233, v233, v235
	v_add_f32_e32 v241, v241, v243
	v_add_f32_e32 v151, v151, v153
	v_add_f32_e32 v159, v159, v161
	v_add_f32_e32 v167, v167, v169
	v_add_f32_e32 v175, v175, v177
	v_add_f32_e32 v221, v221, v223
	v_add_f32_e32 v229, v229, v231
	v_add_f32_e32 v237, v237, v239
	v_add_f32_e32 v245, v245, v247
	v_add_f32_e32 v147, v147, v151
	v_add_f32_e32 v155, v155, v159
	v_add_f32_e32 v163, v163, v167
	v_add_f32_e32 v171, v171, v175
	v_add_f32_e32 v179, v179, v221
	v_add_f32_e32 v225, v225, v229
	v_add_f32_e32 v233, v233, v237
	v_add_f32_e32 v241, v241, v245
	v_fmamk_f32 v248, v248, 0x43800000, v147
	v_fmamk_f32 v249, v249, 0x43800000, v155
	v_fmamk_f32 v250, v250, 0x43800000, v163
	v_fmamk_f32 v251, v251, 0x43800000, v171
	v_fmamk_f32 v180, v180, 0x43800000, v179
	v_fmamk_f32 v181, v181, 0x43800000, v225
	v_fmamk_f32 v182, v182, 0x43800000, v233
	v_fmamk_f32 v252, v252, 0x43800000, v241
	v_fmamk_f32 v248, v248, 0x3a800000, v1
	v_fmamk_f32 v249, v249, 0x3a800000, v1
	v_fmamk_f32 v250, v250, 0x3a800000, v1
	v_fmamk_f32 v251, v251, 0x3a800000, v1
	v_fmamk_f32 v180, v180, 0x3a800000, v1
	v_fmamk_f32 v181, v181, 0x3a800000, v1
	v_fmamk_f32 v182, v182, 0x3a800000, v1
	v_fmamk_f32 v252, v252, 0x3a800000, v1
	v_rsq_f32_e32 v131, v248
	v_rsq_f32_e32 v133, v249
	v_rsq_f32_e32 v135, v250
	v_rsq_f32_e32 v137, v251
	v_rsq_f32_e32 v139, v180
	v_rsq_f32_e32 v141, v181
	v_rsq_f32_e32 v143, v182
	v_rsq_f32_e32 v145, v252
	s_nop 0
	s_mov_b32 s10, 0x0
	s_mov_b32 s11, 0
	v_lshl_add_u64 v[146:147], v[184:185], 0, s[10:11]
	v_pk_add_f32 v[98:99], v[98:99], v[130:131] op_sel_hi:[1,0] neg_lo:[0,1] neg_hi:[0,1]
	v_pk_mul_f32 v[98:99], v[98:99], v[130:131] op_sel:[0,1]
	v_pk_fma_f32 v[98:99], v[186:187], v[98:99], v[202:203]
	v_pk_add_f32 v[100:101], v[100:101], v[130:131] op_sel_hi:[1,0] neg_lo:[0,1] neg_hi:[0,1]
	v_pk_mul_f32 v[100:101], v[100:101], v[130:131] op_sel:[0,1]
	v_pk_fma_f32 v[100:101], v[188:189], v[100:101], v[204:205]
	v_pk_add_f32 v[102:103], v[102:103], v[130:131] op_sel_hi:[1,0] neg_lo:[0,1] neg_hi:[0,1]
	v_pk_mul_f32 v[102:103], v[102:103], v[130:131] op_sel:[0,1]
	v_pk_fma_f32 v[102:103], v[190:191], v[102:103], v[206:207]
	v_pk_add_f32 v[104:105], v[104:105], v[130:131] op_sel_hi:[1,0] neg_lo:[0,1] neg_hi:[0,1]
	v_pk_mul_f32 v[104:105], v[104:105], v[130:131] op_sel:[0,1]
	v_pk_fma_f32 v[104:105], v[192:193], v[104:105], v[208:209]
	global_store_dwordx4 v[146:147], v[98:101], off
	global_store_dwordx4 v[146:147], v[102:105], off offset:16
	s_mov_b32 s10, 0x20000
	s_mov_b32 s11, 0
	v_lshl_add_u64 v[148:149], v[184:185], 0, s[10:11]
	v_pk_add_f32 v[106:107], v[106:107], v[132:133] op_sel_hi:[1,0] neg_lo:[0,1] neg_hi:[0,1]
	v_pk_mul_f32 v[106:107], v[106:107], v[132:133] op_sel:[0,1]
	v_pk_fma_f32 v[106:107], v[186:187], v[106:107], v[202:203]
	v_pk_add_f32 v[108:109], v[108:109], v[132:133] op_sel_hi:[1,0] neg_lo:[0,1] neg_hi:[0,1]
	v_pk_mul_f32 v[108:109], v[108:109], v[132:133] op_sel:[0,1]
	v_pk_fma_f32 v[108:109], v[188:189], v[108:109], v[204:205]
	v_pk_add_f32 v[110:111], v[110:111], v[132:133] op_sel_hi:[1,0] neg_lo:[0,1] neg_hi:[0,1]
	v_pk_mul_f32 v[110:111], v[110:111], v[132:133] op_sel:[0,1]
	v_pk_fma_f32 v[110:111], v[190:191], v[110:111], v[206:207]
	v_pk_add_f32 v[112:113], v[112:113], v[132:133] op_sel_hi:[1,0] neg_lo:[0,1] neg_hi:[0,1]
	v_pk_mul_f32 v[112:113], v[112:113], v[132:133] op_sel:[0,1]
	v_pk_fma_f32 v[112:113], v[192:193], v[112:113], v[208:209]
	global_store_dwordx4 v[148:149], v[106:109], off
	global_store_dwordx4 v[148:149], v[110:113], off offset:16
	s_mov_b32 s10, 0x40000
	s_mov_b32 s11, 0
	v_lshl_add_u64 v[146:147], v[184:185], 0, s[10:11]
	v_pk_add_f32 v[114:115], v[114:115], v[134:135] op_sel_hi:[1,0] neg_lo:[0,1] neg_hi:[0,1]
	v_pk_mul_f32 v[114:115], v[114:115], v[134:135] op_sel:[0,1]
	v_pk_fma_f32 v[114:115], v[186:187], v[114:115], v[202:203]
	v_pk_add_f32 v[116:117], v[116:117], v[134:135] op_sel_hi:[1,0] neg_lo:[0,1] neg_hi:[0,1]
	v_pk_mul_f32 v[116:117], v[116:117], v[134:135] op_sel:[0,1]
	v_pk_fma_f32 v[116:117], v[188:189], v[116:117], v[204:205]
	v_pk_add_f32 v[118:119], v[118:119], v[134:135] op_sel_hi:[1,0] neg_lo:[0,1] neg_hi:[0,1]
	v_pk_mul_f32 v[118:119], v[118:119], v[134:135] op_sel:[0,1]
	v_pk_fma_f32 v[118:119], v[190:191], v[118:119], v[206:207]
	v_pk_add_f32 v[120:121], v[120:121], v[134:135] op_sel_hi:[1,0] neg_lo:[0,1] neg_hi:[0,1]
	v_pk_mul_f32 v[120:121], v[120:121], v[134:135] op_sel:[0,1]
	v_pk_fma_f32 v[120:121], v[192:193], v[120:121], v[208:209]
	global_store_dwordx4 v[146:147], v[114:117], off
	global_store_dwordx4 v[146:147], v[118:121], off offset:16
	s_mov_b32 s10, 0x60000
	s_mov_b32 s11, 0
	v_lshl_add_u64 v[148:149], v[184:185], 0, s[10:11]
	v_pk_add_f32 v[122:123], v[122:123], v[136:137] op_sel_hi:[1,0] neg_lo:[0,1] neg_hi:[0,1]
	v_pk_mul_f32 v[122:123], v[122:123], v[136:137] op_sel:[0,1]
	v_pk_fma_f32 v[122:123], v[186:187], v[122:123], v[202:203]
	v_pk_add_f32 v[124:125], v[124:125], v[136:137] op_sel_hi:[1,0] neg_lo:[0,1] neg_hi:[0,1]
	v_pk_mul_f32 v[124:125], v[124:125], v[136:137] op_sel:[0,1]
	v_pk_fma_f32 v[124:125], v[188:189], v[124:125], v[204:205]
	v_pk_add_f32 v[126:127], v[126:127], v[136:137] op_sel_hi:[1,0] neg_lo:[0,1] neg_hi:[0,1]
	v_pk_mul_f32 v[126:127], v[126:127], v[136:137] op_sel:[0,1]
	v_pk_fma_f32 v[126:127], v[190:191], v[126:127], v[206:207]
	v_pk_add_f32 v[128:129], v[128:129], v[136:137] op_sel_hi:[1,0] neg_lo:[0,1] neg_hi:[0,1]
	v_pk_mul_f32 v[128:129], v[128:129], v[136:137] op_sel:[0,1]
	v_pk_fma_f32 v[128:129], v[192:193], v[128:129], v[208:209]
	global_store_dwordx4 v[148:149], v[122:125], off
	global_store_dwordx4 v[148:149], v[126:129], off offset:16
	s_mov_b32 s10, 0x200
	s_mov_b32 s11, 0
	v_lshl_add_u64 v[146:147], v[184:185], 0, s[10:11]
	v_pk_add_f32 v[66:67], v[66:67], v[130:131] op_sel_hi:[1,0] neg_lo:[0,1] neg_hi:[0,1]
	v_pk_mul_f32 v[66:67], v[66:67], v[130:131] op_sel:[0,1]
	v_pk_fma_f32 v[66:67], v[194:195], v[66:67], v[210:211]
	v_pk_add_f32 v[68:69], v[68:69], v[130:131] op_sel_hi:[1,0] neg_lo:[0,1] neg_hi:[0,1]
	v_pk_mul_f32 v[68:69], v[68:69], v[130:131] op_sel:[0,1]
	v_pk_fma_f32 v[68:69], v[196:197], v[68:69], v[212:213]
	v_pk_add_f32 v[70:71], v[70:71], v[130:131] op_sel_hi:[1,0] neg_lo:[0,1] neg_hi:[0,1]
	v_pk_mul_f32 v[70:71], v[70:71], v[130:131] op_sel:[0,1]
	v_pk_fma_f32 v[70:71], v[198:199], v[70:71], v[214:215]
	v_pk_add_f32 v[72:73], v[72:73], v[130:131] op_sel_hi:[1,0] neg_lo:[0,1] neg_hi:[0,1]
	v_pk_mul_f32 v[72:73], v[72:73], v[130:131] op_sel:[0,1]
	v_pk_fma_f32 v[72:73], v[200:201], v[72:73], v[216:217]
	global_store_dwordx4 v[146:147], v[66:69], off
	global_store_dwordx4 v[146:147], v[70:73], off offset:16
	s_mov_b32 s10, 0x20200
	s_mov_b32 s11, 0
	v_lshl_add_u64 v[148:149], v[184:185], 0, s[10:11]
	v_pk_add_f32 v[74:75], v[74:75], v[132:133] op_sel_hi:[1,0] neg_lo:[0,1] neg_hi:[0,1]
	v_pk_mul_f32 v[74:75], v[74:75], v[132:133] op_sel:[0,1]
	v_pk_fma_f32 v[74:75], v[194:195], v[74:75], v[210:211]
	v_pk_add_f32 v[76:77], v[76:77], v[132:133] op_sel_hi:[1,0] neg_lo:[0,1] neg_hi:[0,1]
	v_pk_mul_f32 v[76:77], v[76:77], v[132:133] op_sel:[0,1]
	v_pk_fma_f32 v[76:77], v[196:197], v[76:77], v[212:213]
	v_pk_add_f32 v[78:79], v[78:79], v[132:133] op_sel_hi:[1,0] neg_lo:[0,1] neg_hi:[0,1]
	v_pk_mul_f32 v[78:79], v[78:79], v[132:133] op_sel:[0,1]
	v_pk_fma_f32 v[78:79], v[198:199], v[78:79], v[214:215]
	v_pk_add_f32 v[80:81], v[80:81], v[132:133] op_sel_hi:[1,0] neg_lo:[0,1] neg_hi:[0,1]
	v_pk_mul_f32 v[80:81], v[80:81], v[132:133] op_sel:[0,1]
	v_pk_fma_f32 v[80:81], v[200:201], v[80:81], v[216:217]
	global_store_dwordx4 v[148:149], v[74:77], off
	global_store_dwordx4 v[148:149], v[78:81], off offset:16
	s_mov_b32 s10, 0x40200
	s_mov_b32 s11, 0
	v_lshl_add_u64 v[146:147], v[184:185], 0, s[10:11]
	v_pk_add_f32 v[82:83], v[82:83], v[134:135] op_sel_hi:[1,0] neg_lo:[0,1] neg_hi:[0,1]
	v_pk_mul_f32 v[82:83], v[82:83], v[134:135] op_sel:[0,1]
	v_pk_fma_f32 v[82:83], v[194:195], v[82:83], v[210:211]
	v_pk_add_f32 v[84:85], v[84:85], v[134:135] op_sel_hi:[1,0] neg_lo:[0,1] neg_hi:[0,1]
	v_pk_mul_f32 v[84:85], v[84:85], v[134:135] op_sel:[0,1]
	v_pk_fma_f32 v[84:85], v[196:197], v[84:85], v[212:213]
	v_pk_add_f32 v[86:87], v[86:87], v[134:135] op_sel_hi:[1,0] neg_lo:[0,1] neg_hi:[0,1]
	v_pk_mul_f32 v[86:87], v[86:87], v[134:135] op_sel:[0,1]
	v_pk_fma_f32 v[86:87], v[198:199], v[86:87], v[214:215]
	v_pk_add_f32 v[88:89], v[88:89], v[134:135] op_sel_hi:[1,0] neg_lo:[0,1] neg_hi:[0,1]
	v_pk_mul_f32 v[88:89], v[88:89], v[134:135] op_sel:[0,1]
	v_pk_fma_f32 v[88:89], v[200:201], v[88:89], v[216:217]
	global_store_dwordx4 v[146:147], v[82:85], off
	global_store_dwordx4 v[146:147], v[86:89], off offset:16
	s_mov_b32 s10, 0x60200
	s_mov_b32 s11, 0
	v_lshl_add_u64 v[148:149], v[184:185], 0, s[10:11]
	v_pk_add_f32 v[90:91], v[90:91], v[136:137] op_sel_hi:[1,0] neg_lo:[0,1] neg_hi:[0,1]
	v_pk_mul_f32 v[90:91], v[90:91], v[136:137] op_sel:[0,1]
	v_pk_fma_f32 v[90:91], v[194:195], v[90:91], v[210:211]
	v_pk_add_f32 v[92:93], v[92:93], v[136:137] op_sel_hi:[1,0] neg_lo:[0,1] neg_hi:[0,1]
	v_pk_mul_f32 v[92:93], v[92:93], v[136:137] op_sel:[0,1]
	v_pk_fma_f32 v[92:93], v[196:197], v[92:93], v[212:213]
	v_pk_add_f32 v[94:95], v[94:95], v[136:137] op_sel_hi:[1,0] neg_lo:[0,1] neg_hi:[0,1]
	v_pk_mul_f32 v[94:95], v[94:95], v[136:137] op_sel:[0,1]
	v_pk_fma_f32 v[94:95], v[198:199], v[94:95], v[214:215]
	v_pk_add_f32 v[96:97], v[96:97], v[136:137] op_sel_hi:[1,0] neg_lo:[0,1] neg_hi:[0,1]
	v_pk_mul_f32 v[96:97], v[96:97], v[136:137] op_sel:[0,1]
	v_pk_fma_f32 v[96:97], v[200:201], v[96:97], v[216:217]
	global_store_dwordx4 v[148:149], v[90:93], off
	global_store_dwordx4 v[148:149], v[94:97], off offset:16
	s_mov_b32 s10, 0x80000
	s_mov_b32 s11, 0
	v_lshl_add_u64 v[146:147], v[184:185], 0, s[10:11]
	v_pk_add_f32 v[34:35], v[34:35], v[138:139] op_sel_hi:[1,0] neg_lo:[0,1] neg_hi:[0,1]
	v_pk_mul_f32 v[34:35], v[34:35], v[138:139] op_sel:[0,1]
	v_pk_fma_f32 v[34:35], v[186:187], v[34:35], v[202:203]
	v_pk_add_f32 v[36:37], v[36:37], v[138:139] op_sel_hi:[1,0] neg_lo:[0,1] neg_hi:[0,1]
	v_pk_mul_f32 v[36:37], v[36:37], v[138:139] op_sel:[0,1]
	v_pk_fma_f32 v[36:37], v[188:189], v[36:37], v[204:205]
	v_pk_add_f32 v[38:39], v[38:39], v[138:139] op_sel_hi:[1,0] neg_lo:[0,1] neg_hi:[0,1]
	v_pk_mul_f32 v[38:39], v[38:39], v[138:139] op_sel:[0,1]
	v_pk_fma_f32 v[38:39], v[190:191], v[38:39], v[206:207]
	v_pk_add_f32 v[40:41], v[40:41], v[138:139] op_sel_hi:[1,0] neg_lo:[0,1] neg_hi:[0,1]
	v_pk_mul_f32 v[40:41], v[40:41], v[138:139] op_sel:[0,1]
	v_pk_fma_f32 v[40:41], v[192:193], v[40:41], v[208:209]
	global_store_dwordx4 v[146:147], v[34:37], off
	global_store_dwordx4 v[146:147], v[38:41], off offset:16
	s_mov_b32 s10, 0xa0000
	s_mov_b32 s11, 0
	v_lshl_add_u64 v[148:149], v[184:185], 0, s[10:11]
	v_pk_add_f32 v[42:43], v[42:43], v[140:141] op_sel_hi:[1,0] neg_lo:[0,1] neg_hi:[0,1]
	v_pk_mul_f32 v[42:43], v[42:43], v[140:141] op_sel:[0,1]
	v_pk_fma_f32 v[42:43], v[186:187], v[42:43], v[202:203]
	v_pk_add_f32 v[44:45], v[44:45], v[140:141] op_sel_hi:[1,0] neg_lo:[0,1] neg_hi:[0,1]
	v_pk_mul_f32 v[44:45], v[44:45], v[140:141] op_sel:[0,1]
	v_pk_fma_f32 v[44:45], v[188:189], v[44:45], v[204:205]
	v_pk_add_f32 v[46:47], v[46:47], v[140:141] op_sel_hi:[1,0] neg_lo:[0,1] neg_hi:[0,1]
	v_pk_mul_f32 v[46:47], v[46:47], v[140:141] op_sel:[0,1]
	v_pk_fma_f32 v[46:47], v[190:191], v[46:47], v[206:207]
	v_pk_add_f32 v[48:49], v[48:49], v[140:141] op_sel_hi:[1,0] neg_lo:[0,1] neg_hi:[0,1]
	v_pk_mul_f32 v[48:49], v[48:49], v[140:141] op_sel:[0,1]
	v_pk_fma_f32 v[48:49], v[192:193], v[48:49], v[208:209]
	global_store_dwordx4 v[148:149], v[42:45], off
	global_store_dwordx4 v[148:149], v[46:49], off offset:16
	s_mov_b32 s10, 0xc0000
	s_mov_b32 s11, 0
	v_lshl_add_u64 v[146:147], v[184:185], 0, s[10:11]
	v_pk_add_f32 v[50:51], v[50:51], v[142:143] op_sel_hi:[1,0] neg_lo:[0,1] neg_hi:[0,1]
	v_pk_mul_f32 v[50:51], v[50:51], v[142:143] op_sel:[0,1]
	v_pk_fma_f32 v[50:51], v[186:187], v[50:51], v[202:203]
	v_pk_add_f32 v[52:53], v[52:53], v[142:143] op_sel_hi:[1,0] neg_lo:[0,1] neg_hi:[0,1]
	v_pk_mul_f32 v[52:53], v[52:53], v[142:143] op_sel:[0,1]
	v_pk_fma_f32 v[52:53], v[188:189], v[52:53], v[204:205]
	v_pk_add_f32 v[54:55], v[54:55], v[142:143] op_sel_hi:[1,0] neg_lo:[0,1] neg_hi:[0,1]
	v_pk_mul_f32 v[54:55], v[54:55], v[142:143] op_sel:[0,1]
	v_pk_fma_f32 v[54:55], v[190:191], v[54:55], v[206:207]
	v_pk_add_f32 v[56:57], v[56:57], v[142:143] op_sel_hi:[1,0] neg_lo:[0,1] neg_hi:[0,1]
	v_pk_mul_f32 v[56:57], v[56:57], v[142:143] op_sel:[0,1]
	v_pk_fma_f32 v[56:57], v[192:193], v[56:57], v[208:209]
	global_store_dwordx4 v[146:147], v[50:53], off
	global_store_dwordx4 v[146:147], v[54:57], off offset:16
	s_mov_b32 s10, 0xe0000
	s_mov_b32 s11, 0
	v_lshl_add_u64 v[148:149], v[184:185], 0, s[10:11]
	v_pk_add_f32 v[58:59], v[58:59], v[144:145] op_sel_hi:[1,0] neg_lo:[0,1] neg_hi:[0,1]
	v_pk_mul_f32 v[58:59], v[58:59], v[144:145] op_sel:[0,1]
	v_pk_fma_f32 v[58:59], v[186:187], v[58:59], v[202:203]
	v_pk_add_f32 v[60:61], v[60:61], v[144:145] op_sel_hi:[1,0] neg_lo:[0,1] neg_hi:[0,1]
	v_pk_mul_f32 v[60:61], v[60:61], v[144:145] op_sel:[0,1]
	v_pk_fma_f32 v[60:61], v[188:189], v[60:61], v[204:205]
	v_pk_add_f32 v[62:63], v[62:63], v[144:145] op_sel_hi:[1,0] neg_lo:[0,1] neg_hi:[0,1]
	v_pk_mul_f32 v[62:63], v[62:63], v[144:145] op_sel:[0,1]
	v_pk_fma_f32 v[62:63], v[190:191], v[62:63], v[206:207]
	v_pk_add_f32 v[64:65], v[64:65], v[144:145] op_sel_hi:[1,0] neg_lo:[0,1] neg_hi:[0,1]
	v_pk_mul_f32 v[64:65], v[64:65], v[144:145] op_sel:[0,1]
	v_pk_fma_f32 v[64:65], v[192:193], v[64:65], v[208:209]
	global_store_dwordx4 v[148:149], v[58:61], off
	global_store_dwordx4 v[148:149], v[62:65], off offset:16
	s_mov_b32 s10, 0x80200
	s_mov_b32 s11, 0
	v_lshl_add_u64 v[146:147], v[184:185], 0, s[10:11]
	v_pk_add_f32 v[2:3], v[2:3], v[138:139] op_sel_hi:[1,0] neg_lo:[0,1] neg_hi:[0,1]
	v_pk_mul_f32 v[2:3], v[2:3], v[138:139] op_sel:[0,1]
	v_pk_fma_f32 v[2:3], v[194:195], v[2:3], v[210:211]
	v_pk_add_f32 v[4:5], v[4:5], v[138:139] op_sel_hi:[1,0] neg_lo:[0,1] neg_hi:[0,1]
	v_pk_mul_f32 v[4:5], v[4:5], v[138:139] op_sel:[0,1]
	v_pk_fma_f32 v[4:5], v[196:197], v[4:5], v[212:213]
	v_pk_add_f32 v[6:7], v[6:7], v[138:139] op_sel_hi:[1,0] neg_lo:[0,1] neg_hi:[0,1]
	v_pk_mul_f32 v[6:7], v[6:7], v[138:139] op_sel:[0,1]
	v_pk_fma_f32 v[6:7], v[198:199], v[6:7], v[214:215]
	v_pk_add_f32 v[8:9], v[8:9], v[138:139] op_sel_hi:[1,0] neg_lo:[0,1] neg_hi:[0,1]
	v_pk_mul_f32 v[8:9], v[8:9], v[138:139] op_sel:[0,1]
	v_pk_fma_f32 v[8:9], v[200:201], v[8:9], v[216:217]
	global_store_dwordx4 v[146:147], v[2:5], off
	global_store_dwordx4 v[146:147], v[6:9], off offset:16
	s_mov_b32 s10, 0xa0200
	s_mov_b32 s11, 0
	v_lshl_add_u64 v[148:149], v[184:185], 0, s[10:11]
	v_pk_add_f32 v[10:11], v[10:11], v[140:141] op_sel_hi:[1,0] neg_lo:[0,1] neg_hi:[0,1]
	v_pk_mul_f32 v[10:11], v[10:11], v[140:141] op_sel:[0,1]
	v_pk_fma_f32 v[10:11], v[194:195], v[10:11], v[210:211]
	v_pk_add_f32 v[12:13], v[12:13], v[140:141] op_sel_hi:[1,0] neg_lo:[0,1] neg_hi:[0,1]
	v_pk_mul_f32 v[12:13], v[12:13], v[140:141] op_sel:[0,1]
	v_pk_fma_f32 v[12:13], v[196:197], v[12:13], v[212:213]
	v_pk_add_f32 v[14:15], v[14:15], v[140:141] op_sel_hi:[1,0] neg_lo:[0,1] neg_hi:[0,1]
	v_pk_mul_f32 v[14:15], v[14:15], v[140:141] op_sel:[0,1]
	v_pk_fma_f32 v[14:15], v[198:199], v[14:15], v[214:215]
	v_pk_add_f32 v[16:17], v[16:17], v[140:141] op_sel_hi:[1,0] neg_lo:[0,1] neg_hi:[0,1]
	v_pk_mul_f32 v[16:17], v[16:17], v[140:141] op_sel:[0,1]
	v_pk_fma_f32 v[16:17], v[200:201], v[16:17], v[216:217]
	global_store_dwordx4 v[148:149], v[10:13], off
	global_store_dwordx4 v[148:149], v[14:17], off offset:16
	s_mov_b32 s10, 0xc0200
	s_mov_b32 s11, 0
	v_lshl_add_u64 v[146:147], v[184:185], 0, s[10:11]
	v_pk_add_f32 v[18:19], v[18:19], v[142:143] op_sel_hi:[1,0] neg_lo:[0,1] neg_hi:[0,1]
	v_pk_mul_f32 v[18:19], v[18:19], v[142:143] op_sel:[0,1]
	v_pk_fma_f32 v[18:19], v[194:195], v[18:19], v[210:211]
	v_pk_add_f32 v[20:21], v[20:21], v[142:143] op_sel_hi:[1,0] neg_lo:[0,1] neg_hi:[0,1]
	v_pk_mul_f32 v[20:21], v[20:21], v[142:143] op_sel:[0,1]
	v_pk_fma_f32 v[20:21], v[196:197], v[20:21], v[212:213]
	v_pk_add_f32 v[22:23], v[22:23], v[142:143] op_sel_hi:[1,0] neg_lo:[0,1] neg_hi:[0,1]
	v_pk_mul_f32 v[22:23], v[22:23], v[142:143] op_sel:[0,1]
	v_pk_fma_f32 v[22:23], v[198:199], v[22:23], v[214:215]
	v_pk_add_f32 v[24:25], v[24:25], v[142:143] op_sel_hi:[1,0] neg_lo:[0,1] neg_hi:[0,1]
	v_pk_mul_f32 v[24:25], v[24:25], v[142:143] op_sel:[0,1]
	v_pk_fma_f32 v[24:25], v[200:201], v[24:25], v[216:217]
	global_store_dwordx4 v[146:147], v[18:21], off
	global_store_dwordx4 v[146:147], v[22:25], off offset:16
	s_mov_b32 s10, 0xe0200
	s_mov_b32 s11, 0
	v_lshl_add_u64 v[148:149], v[184:185], 0, s[10:11]
	v_pk_add_f32 v[26:27], v[26:27], v[144:145] op_sel_hi:[1,0] neg_lo:[0,1] neg_hi:[0,1]
	v_pk_mul_f32 v[26:27], v[26:27], v[144:145] op_sel:[0,1]
	v_pk_fma_f32 v[26:27], v[194:195], v[26:27], v[210:211]
	v_pk_add_f32 v[28:29], v[28:29], v[144:145] op_sel_hi:[1,0] neg_lo:[0,1] neg_hi:[0,1]
	v_pk_mul_f32 v[28:29], v[28:29], v[144:145] op_sel:[0,1]
	v_pk_fma_f32 v[28:29], v[196:197], v[28:29], v[212:213]
	v_pk_add_f32 v[30:31], v[30:31], v[144:145] op_sel_hi:[1,0] neg_lo:[0,1] neg_hi:[0,1]
	v_pk_mul_f32 v[30:31], v[30:31], v[144:145] op_sel:[0,1]
	v_pk_fma_f32 v[30:31], v[198:199], v[30:31], v[214:215]
	v_pk_add_f32 v[32:33], v[32:33], v[144:145] op_sel_hi:[1,0] neg_lo:[0,1] neg_hi:[0,1]
	v_pk_mul_f32 v[32:33], v[32:33], v[144:145] op_sel:[0,1]
	v_pk_fma_f32 v[32:33], v[200:201], v[32:33], v[216:217]
	global_store_dwordx4 v[148:149], v[26:29], off
	global_store_dwordx4 v[148:149], v[30:33], off offset:16
	s_endpgm

.LBB0_2000:
	s_waitcnt vmcnt(0)
.LBB0_2055:
	s_endpgm
